# hand-written pipelined SSD combine (3 rows in flight, coalesced)
# speedup vs baseline: 1.0207x; 1.0056x over previous
; __device__ __forceinline__ int ltid() { int t = threadIdx.x; asm volatile("" : "+v"(t)); return t; }
; __device__ __forceinline__ int lbid() { int t = blockIdx.x; asm volatile("" : "+s"(t)); return t; }
; #define wt16(p, v) wt16b(WSB, (p), (v))
; __device__ __forceinline__ u32x4 pack8(const float (&f)[8]) { u32x4 v; v.x = cvt_pk_bf16(f[0], f[1]); v.y = cvt_pk_bf16(f[2], f[3]); v.z = cvt_pk_bf16(f[4], f[5]); v.w = cvt_pk_bf16(f[6], f[7]); return v; }
; __device__ __forceinline__ float silu_f(float x) { return x * __builtin_amdgcn_rcpf(1.f + __expf(-x)); }
; __device__ __forceinline__ void ssd_combine_rows(CArgs a, int G) {
;     const int lane = ltid() & 63, wave = ltid() >> 6;
;     const int gw = lbid() * NWAVES + wave, NGW = G * NWAVES;
;     const unsigned char* WSB = a->ws;
;     const bf16_t* U = (const bf16_t*)(a->ws + WS_U); bf16_t* Y = (bf16_t*)(a->ws + WS_Y);
;     const bf16_t* yb = (const bf16_t*)(a->ws + WS_YF);
;     const int c0 = lane * 16;
;     auto load = [&](int row, u32x4 (&raw)[6]) {
; #pragma unroll
;         for (int hf = 0; hf < 2; ++hf) { raw[3 * hf] = *(const u32x4*)(Y + (size_t)row * 2048 + c0 + 8 * hf); raw[3 * hf + 1] = *(const u32x4*)(yb + (size_t)row * 1024 + c0 + 8 * hf);
;             raw[3 * hf + 2] = *(const u32x4*)(U + (size_t)row * NU + UZ + c0 + 8 * hf); }
;     };
;     auto finish = [&](int row, const u32x4 (&raw)[6]) {
;         float g[16]; float ss = 0.f;
; #pragma unroll
;         for (int hf = 0; hf < 2; ++hf) {
;             float f[8], bb[8], z[8];
;             unpack8(raw[3 * hf], f); unpack8(raw[3 * hf + 1], bb); unpack8(raw[3 * hf + 2], z);
; #pragma unroll
;             for (int e = 0; e < 8; ++e) { const float y = (f[e] + bb[e]) * silu_f(z[e]); g[8 * hf + e] = y; ss += y * y; }
;         }
;         ss += __shfl_xor(ss, 1); ss += __shfl_xor(ss, 2); ss += __shfl_xor(ss, 4); ss += __shfl_xor(ss, 8); ss += __shfl_xor(ss, 16);
;         const float r = rsqrtf(ss * (1.f / 512.f) + EPS);
;         float o0[8], o1[8];
; #pragma unroll
;         for (int e = 0; e < 8; ++e) { o0[e] = g[e] * r; o1[e] = g[8 + e] * r; }
;         wt16(Y + (size_t)row * 2048 + c0, pack8(o0)); wt16(Y + (size_t)row * 2048 + c0 + 8, pack8(o1));
;     };
.LBB0_83:
	v_readlane_b32 s2, v255, 42
	s_nop 3
	s_cmp_eq_u32 s2, 2
	s_cbranch_scc1 .Lp5_done
	s_load_dwordx2 s[60:61], s[6:7], 0xe8
	v_readfirstlane_b32 s10, v244
	v_and_b32_e32 v2, 63, v244
	v_lshlrev_b32_e32 v2, 4, v2
	v_readlane_b32 s11, v253, 0
	s_lshr_b32 s10, s10, 6
	s_nop 3
	s_lshl_b32 s11, s11, 3
	s_add_i32 s10, s10, s11
	s_lshl_b32 s11, s64, 3
	s_waitcnt lgkmcnt(0)
	s_and_b32 s61, s61, 0xffff
	s_cmp_lt_u32 s10, 0x4000
	s_cbranch_scc0 .Lcmb_done
	s_lshl_b32 s16, s10, 12
	s_add_u32 s16, s16, 0x10a00000
	s_lshl_b32 s17, s10, 11
	s_add_u32 s17, s17, 0x18a00000
	s_mul_i32 s18, s10, 0x2400
	s_add_u32 s18, s18, 0x3a00000
	buffer_load_dwordx4 v[8:11], v2, s[60:63], s16 offen
	buffer_load_dwordx4 v[12:15], v2, s[60:63], s16 offen offset:1024
	buffer_load_dwordx4 v[16:19], v2, s[60:63], s17 offen
	buffer_load_dwordx4 v[20:23], v2, s[60:63], s17 offen offset:1024
	buffer_load_dwordx4 v[24:27], v2, s[60:63], s18 offen
	buffer_load_dwordx4 v[28:31], v2, s[60:63], s18 offen offset:1024
	s_mul_i32 s12, s11, 1
	s_add_i32 s12, s10, s12
	s_cmp_lt_u32 s12, 0x4000
	s_cselect_b32 s12, s12, s10
	s_lshl_b32 s16, s12, 12
	s_add_u32 s16, s16, 0x10a00000
	s_lshl_b32 s17, s12, 11
	s_add_u32 s17, s17, 0x18a00000
	s_mul_i32 s18, s12, 0x2400
	s_add_u32 s18, s18, 0x3a00000
	buffer_load_dwordx4 v[32:35], v2, s[60:63], s16 offen
	buffer_load_dwordx4 v[36:39], v2, s[60:63], s16 offen offset:1024
	buffer_load_dwordx4 v[40:43], v2, s[60:63], s17 offen
	buffer_load_dwordx4 v[44:47], v2, s[60:63], s17 offen offset:1024
	buffer_load_dwordx4 v[48:51], v2, s[60:63], s18 offen
	buffer_load_dwordx4 v[52:55], v2, s[60:63], s18 offen offset:1024
	s_mul_i32 s12, s11, 2
	s_add_i32 s12, s10, s12
	s_cmp_lt_u32 s12, 0x4000
	s_cselect_b32 s12, s12, s10
	s_lshl_b32 s16, s12, 12
	s_add_u32 s16, s16, 0x10a00000
	s_lshl_b32 s17, s12, 11
	s_add_u32 s17, s17, 0x18a00000
	s_mul_i32 s18, s12, 0x2400
	s_add_u32 s18, s18, 0x3a00000
	buffer_load_dwordx4 v[56:59], v2, s[60:63], s16 offen
	buffer_load_dwordx4 v[60:63], v2, s[60:63], s16 offen offset:1024
	buffer_load_dwordx4 v[64:67], v2, s[60:63], s17 offen
	buffer_load_dwordx4 v[68:71], v2, s[60:63], s17 offen offset:1024
	buffer_load_dwordx4 v[72:75], v2, s[60:63], s18 offen
	buffer_load_dwordx4 v[76:79], v2, s[60:63], s18 offen offset:1024
	s_waitcnt vmcnt(12)
	v_lshlrev_b32_e32 v96, 16, v24
	v_and_b32_e32 v97, 0xffff0000, v24
	v_lshlrev_b32_e32 v98, 16, v25
	v_and_b32_e32 v99, 0xffff0000, v25
	v_lshlrev_b32_e32 v100, 16, v26
	v_and_b32_e32 v101, 0xffff0000, v26
	v_lshlrev_b32_e32 v102, 16, v27
	v_and_b32_e32 v103, 0xffff0000, v27
	v_mul_f32_e32 v104, 0xbfb8aa3b, v96
	v_mul_f32_e32 v105, 0xbfb8aa3b, v97
	v_mul_f32_e32 v106, 0xbfb8aa3b, v98
	v_mul_f32_e32 v107, 0xbfb8aa3b, v99
	v_mul_f32_e32 v108, 0xbfb8aa3b, v100
	v_mul_f32_e32 v109, 0xbfb8aa3b, v101
	v_mul_f32_e32 v110, 0xbfb8aa3b, v102
	v_mul_f32_e32 v111, 0xbfb8aa3b, v103
	v_exp_f32_e32 v104, v104
	v_exp_f32_e32 v105, v105
	v_exp_f32_e32 v106, v106
	v_exp_f32_e32 v107, v107
	v_exp_f32_e32 v108, v108
	v_exp_f32_e32 v109, v109
	v_exp_f32_e32 v110, v110
	v_exp_f32_e32 v111, v111
	v_lshlrev_b32_e32 v112, 16, v8
	v_and_b32_e32 v113, 0xffff0000, v8
	v_lshlrev_b32_e32 v114, 16, v9
	v_and_b32_e32 v115, 0xffff0000, v9
	v_lshlrev_b32_e32 v116, 16, v10
	v_and_b32_e32 v117, 0xffff0000, v10
	v_lshlrev_b32_e32 v118, 16, v11
	v_and_b32_e32 v119, 0xffff0000, v11
	v_lshlrev_b32_e32 v120, 16, v16
	v_and_b32_e32 v121, 0xffff0000, v16
	v_lshlrev_b32_e32 v122, 16, v17
	v_and_b32_e32 v123, 0xffff0000, v17
	v_lshlrev_b32_e32 v124, 16, v18
	v_and_b32_e32 v125, 0xffff0000, v18
	v_lshlrev_b32_e32 v126, 16, v19
	v_and_b32_e32 v127, 0xffff0000, v19
	v_add_f32_e32 v112, v112, v120
	v_add_f32_e32 v113, v113, v121
	v_add_f32_e32 v114, v114, v122
	v_add_f32_e32 v115, v115, v123
	v_add_f32_e32 v116, v116, v124
	v_add_f32_e32 v117, v117, v125
	v_add_f32_e32 v118, v118, v126
	v_add_f32_e32 v119, v119, v127
	v_add_f32_e32 v104, 1.0, v104
	v_add_f32_e32 v105, 1.0, v105
	v_add_f32_e32 v106, 1.0, v106
	v_add_f32_e32 v107, 1.0, v107
	v_add_f32_e32 v108, 1.0, v108
	v_add_f32_e32 v109, 1.0, v109
	v_add_f32_e32 v110, 1.0, v110
	v_add_f32_e32 v111, 1.0, v111
	v_rcp_f32_e32 v104, v104
	v_rcp_f32_e32 v105, v105
	v_rcp_f32_e32 v106, v106
	v_rcp_f32_e32 v107, v107
	v_rcp_f32_e32 v108, v108
	v_rcp_f32_e32 v109, v109
	v_rcp_f32_e32 v110, v110
	v_rcp_f32_e32 v111, v111
	v_mul_f32_e32 v96, v96, v104
	v_mul_f32_e32 v97, v97, v105
	v_mul_f32_e32 v98, v98, v106
	v_mul_f32_e32 v99, v99, v107
	v_mul_f32_e32 v100, v100, v108
	v_mul_f32_e32 v101, v101, v109
	v_mul_f32_e32 v102, v102, v110
	v_mul_f32_e32 v103, v103, v111
	v_mul_f32_e32 v80, v112, v96
	v_mul_f32_e32 v81, v113, v97
	v_mul_f32_e32 v82, v114, v98
	v_mul_f32_e32 v83, v115, v99
	v_mul_f32_e32 v84, v116, v100
	v_mul_f32_e32 v85, v117, v101
	v_mul_f32_e32 v86, v118, v102
	v_mul_f32_e32 v87, v119, v103
	v_mul_f32_e32 v128, v80, v80
	v_fmac_f32_e32 v128, v81, v81
	v_fmac_f32_e32 v128, v82, v82
	v_fmac_f32_e32 v128, v83, v83
	v_fmac_f32_e32 v128, v84, v84
	v_fmac_f32_e32 v128, v85, v85
	v_fmac_f32_e32 v128, v86, v86
	v_fmac_f32_e32 v128, v87, v87
	v_lshlrev_b32_e32 v96, 16, v28
	v_and_b32_e32 v97, 0xffff0000, v28
	v_lshlrev_b32_e32 v98, 16, v29
	v_and_b32_e32 v99, 0xffff0000, v29
	v_lshlrev_b32_e32 v100, 16, v30
	v_and_b32_e32 v101, 0xffff0000, v30
	v_lshlrev_b32_e32 v102, 16, v31
	v_and_b32_e32 v103, 0xffff0000, v31
	v_mul_f32_e32 v104, 0xbfb8aa3b, v96
	v_mul_f32_e32 v105, 0xbfb8aa3b, v97
	v_mul_f32_e32 v106, 0xbfb8aa3b, v98
	v_mul_f32_e32 v107, 0xbfb8aa3b, v99
	v_mul_f32_e32 v108, 0xbfb8aa3b, v100
	v_mul_f32_e32 v109, 0xbfb8aa3b, v101
	v_mul_f32_e32 v110, 0xbfb8aa3b, v102
; #define wt16(p, v) wt16b(WSB, (p), (v))
; __device__ __forceinline__ u32x4 pack8(const float (&f)[8]) { u32x4 v; v.x = cvt_pk_bf16(f[0], f[1]); v.y = cvt_pk_bf16(f[2], f[3]); v.z = cvt_pk_bf16(f[4], f[5]); v.w = cvt_pk_bf16(f[6], f[7]); return v; }
; __device__ __forceinline__ float silu_f(float x) { return x * __builtin_amdgcn_rcpf(1.f + __expf(-x)); }
; __device__ __forceinline__ void ssd_combine_rows(CArgs a, int G) {
;     ...
;     auto finish = [&](int row, const u32x4 (&raw)[6]) {
;         float g[16]; float ss = 0.f;
; #pragma unroll
;         for (int hf = 0; hf < 2; ++hf) {
;             float f[8], bb[8], z[8];
;             unpack8(raw[3 * hf], f); unpack8(raw[3 * hf + 1], bb); unpack8(raw[3 * hf + 2], z);
; #pragma unroll
;             for (int e = 0; e < 8; ++e) { const float y = (f[e] + bb[e]) * silu_f(z[e]); g[8 * hf + e] = y; ss += y * y; }
;         }
;         ss += __shfl_xor(ss, 1); ss += __shfl_xor(ss, 2); ss += __shfl_xor(ss, 4); ss += __shfl_xor(ss, 8); ss += __shfl_xor(ss, 16);
;         const float r = rsqrtf(ss * (1.f / 512.f) + EPS);
;         float o0[8], o1[8];
; #pragma unroll
;         for (int e = 0; e < 8; ++e) { o0[e] = g[e] * r; o1[e] = g[8 + e] * r; }
;         wt16(Y + (size_t)row * 2048 + c0, pack8(o0)); wt16(Y + (size_t)row * 2048 + c0 + 8, pack8(o1));
;     };
	v_mul_f32_e32 v111, 0xbfb8aa3b, v103
	v_exp_f32_e32 v104, v104
	v_exp_f32_e32 v105, v105
	v_exp_f32_e32 v106, v106
	v_exp_f32_e32 v107, v107
	v_exp_f32_e32 v108, v108
	v_exp_f32_e32 v109, v109
	v_exp_f32_e32 v110, v110
	v_exp_f32_e32 v111, v111
	v_lshlrev_b32_e32 v112, 16, v12
	v_and_b32_e32 v113, 0xffff0000, v12
	v_lshlrev_b32_e32 v114, 16, v13
	v_and_b32_e32 v115, 0xffff0000, v13
	v_lshlrev_b32_e32 v116, 16, v14
	v_and_b32_e32 v117, 0xffff0000, v14
	v_lshlrev_b32_e32 v118, 16, v15
	v_and_b32_e32 v119, 0xffff0000, v15
	v_lshlrev_b32_e32 v120, 16, v20
	v_and_b32_e32 v121, 0xffff0000, v20
	v_lshlrev_b32_e32 v122, 16, v21
	v_and_b32_e32 v123, 0xffff0000, v21
	v_lshlrev_b32_e32 v124, 16, v22
	v_and_b32_e32 v125, 0xffff0000, v22
	v_lshlrev_b32_e32 v126, 16, v23
	v_and_b32_e32 v127, 0xffff0000, v23
	v_add_f32_e32 v112, v112, v120
	v_add_f32_e32 v113, v113, v121
	v_add_f32_e32 v114, v114, v122
	v_add_f32_e32 v115, v115, v123
	v_add_f32_e32 v116, v116, v124
	v_add_f32_e32 v117, v117, v125
	v_add_f32_e32 v118, v118, v126
	v_add_f32_e32 v119, v119, v127
	v_add_f32_e32 v104, 1.0, v104
	v_add_f32_e32 v105, 1.0, v105
	v_add_f32_e32 v106, 1.0, v106
	v_add_f32_e32 v107, 1.0, v107
	v_add_f32_e32 v108, 1.0, v108
	v_add_f32_e32 v109, 1.0, v109
	v_add_f32_e32 v110, 1.0, v110
	v_add_f32_e32 v111, 1.0, v111
	v_rcp_f32_e32 v104, v104
	v_rcp_f32_e32 v105, v105
	v_rcp_f32_e32 v106, v106
	v_rcp_f32_e32 v107, v107
	v_rcp_f32_e32 v108, v108
	v_rcp_f32_e32 v109, v109
	v_rcp_f32_e32 v110, v110
	v_rcp_f32_e32 v111, v111
	v_mul_f32_e32 v96, v96, v104
	v_mul_f32_e32 v97, v97, v105
	v_mul_f32_e32 v98, v98, v106
	v_mul_f32_e32 v99, v99, v107
	v_mul_f32_e32 v100, v100, v108
	v_mul_f32_e32 v101, v101, v109
	v_mul_f32_e32 v102, v102, v110
	v_mul_f32_e32 v103, v103, v111
	v_mul_f32_e32 v88, v112, v96
	v_mul_f32_e32 v89, v113, v97
	v_mul_f32_e32 v90, v114, v98
	v_mul_f32_e32 v91, v115, v99
	v_mul_f32_e32 v92, v116, v100
	v_mul_f32_e32 v93, v117, v101
	v_mul_f32_e32 v94, v118, v102
	v_mul_f32_e32 v95, v119, v103
	v_mul_f32_e32 v129, v88, v88
	v_fmac_f32_e32 v129, v89, v89
	v_fmac_f32_e32 v129, v90, v90
	v_fmac_f32_e32 v129, v91, v91
	v_fmac_f32_e32 v129, v92, v92
	v_fmac_f32_e32 v129, v93, v93
	v_fmac_f32_e32 v129, v94, v94
	v_fmac_f32_e32 v129, v95, v95
	s_nop 1
	v_add_f32_dpp v128, v128, v128 row_shr:1 row_mask:0xf bank_mask:0xf bound_ctrl:0
	v_add_f32_dpp v129, v129, v129 row_shr:1 row_mask:0xf bank_mask:0xf bound_ctrl:0
	s_nop 0
	v_add_f32_dpp v128, v128, v128 row_shr:2 row_mask:0xf bank_mask:0xf bound_ctrl:0
	v_add_f32_dpp v129, v129, v129 row_shr:2 row_mask:0xf bank_mask:0xf bound_ctrl:0
	s_nop 0
	v_add_f32_dpp v128, v128, v128 row_shr:4 row_mask:0xf bank_mask:0xf bound_ctrl:0
	v_add_f32_dpp v129, v129, v129 row_shr:4 row_mask:0xf bank_mask:0xf bound_ctrl:0
	s_nop 0
	v_add_f32_dpp v128, v128, v128 row_shr:8 row_mask:0xf bank_mask:0xf bound_ctrl:0
	v_add_f32_dpp v129, v129, v129 row_shr:8 row_mask:0xf bank_mask:0xf bound_ctrl:0
	s_nop 0
	v_add_f32_dpp v128, v128, v128 row_bcast:15 row_mask:0xa bank_mask:0xf
	v_add_f32_dpp v129, v129, v129 row_bcast:15 row_mask:0xa bank_mask:0xf
	s_nop 0
	v_add_f32_dpp v128, v128, v128 row_bcast:31 row_mask:0xc bank_mask:0xf
	v_add_f32_dpp v129, v129, v129 row_bcast:31 row_mask:0xc bank_mask:0xf
	s_nop 0
	s_nop 0
	v_readlane_b32 s20, v128, 63
	v_readlane_b32 s21, v129, 63
	s_nop 1
	v_mov_b32_e32 v130, s20
	v_mov_b32_e32 v131, s21
	v_fmamk_f32 v130, v130, 0x3b000000, v245
	v_fmamk_f32 v131, v131, 0x3b000000, v245
	v_rsq_f32_e32 v130, v130
	v_rsq_f32_e32 v131, v131
	s_nop 0
	v_mul_f32_e32 v80, v80, v130
	v_mul_f32_e32 v81, v81, v130
	v_mul_f32_e32 v82, v82, v130
	v_mul_f32_e32 v83, v83, v130
	v_mul_f32_e32 v84, v84, v130
	v_mul_f32_e32 v85, v85, v130
	v_mul_f32_e32 v86, v86, v130
	v_mul_f32_e32 v87, v87, v130
	v_cvt_pk_bf16_f32 v80, v80, v81
	v_cvt_pk_bf16_f32 v81, v82, v83
	v_cvt_pk_bf16_f32 v82, v84, v85
	v_cvt_pk_bf16_f32 v83, v86, v87
	v_mul_f32_e32 v88, v88, v131
	v_mul_f32_e32 v89, v89, v131
	v_mul_f32_e32 v90, v90, v131
	v_mul_f32_e32 v91, v91, v131
	v_mul_f32_e32 v92, v92, v131
	v_mul_f32_e32 v93, v93, v131
	v_mul_f32_e32 v94, v94, v131
	v_mul_f32_e32 v95, v95, v131
	v_cvt_pk_bf16_f32 v88, v88, v89
	v_cvt_pk_bf16_f32 v89, v90, v91
	v_cvt_pk_bf16_f32 v90, v92, v93
	v_cvt_pk_bf16_f32 v91, v94, v95
	s_lshl_b32 s19, s10, 12
	s_add_u32 s19, s19, 0x10a00000
	buffer_store_dwordx4 v[80:83], v2, s[60:63], s19 offen sc1
	buffer_store_dwordx4 v[88:91], v2, s[60:63], s19 offen offset:1024 sc1
	s_mul_i32 s12, s11, 3
	s_add_i32 s12, s10, s12
	s_cmp_lt_u32 s12, 0x4000
	s_cselect_b32 s12, s12, s10
	s_lshl_b32 s16, s12, 12
	s_add_u32 s16, s16, 0x10a00000
	s_lshl_b32 s17, s12, 11
	s_add_u32 s17, s17, 0x18a00000
	s_mul_i32 s18, s12, 0x2400
	s_add_u32 s18, s18, 0x3a00000
	buffer_load_dwordx4 v[8:11], v2, s[60:63], s16 offen
	buffer_load_dwordx4 v[12:15], v2, s[60:63], s16 offen offset:1024
	buffer_load_dwordx4 v[16:19], v2, s[60:63], s17 offen
	buffer_load_dwordx4 v[20:23], v2, s[60:63], s17 offen offset:1024
	buffer_load_dwordx4 v[24:27], v2, s[60:63], s18 offen
	buffer_load_dwordx4 v[28:31], v2, s[60:63], s18 offen offset:1024
	s_add_i32 s10, s10, s11
	s_cmp_lt_u32 s10, 0x4000
	s_cbranch_scc0 .Lcmb_done
; #define wt16(p, v) wt16b(WSB, (p), (v))
; __device__ __forceinline__ u32x4 pack8(const float (&f)[8]) { u32x4 v; v.x = cvt_pk_bf16(f[0], f[1]); v.y = cvt_pk_bf16(f[2], f[3]); v.z = cvt_pk_bf16(f[4], f[5]); v.w = cvt_pk_bf16(f[6], f[7]); return v; }
; __device__ __forceinline__ float silu_f(float x) { return x * __builtin_amdgcn_rcpf(1.f + __expf(-x)); }
; __device__ __forceinline__ void ssd_combine_rows(CArgs a, int G) {
;     ...
;     auto finish = [&](int row, const u32x4 (&raw)[6]) {
;         float g[16]; float ss = 0.f;
; #pragma unroll
;         for (int hf = 0; hf < 2; ++hf) {
;             float f[8], bb[8], z[8];
;             unpack8(raw[3 * hf], f); unpack8(raw[3 * hf + 1], bb); unpack8(raw[3 * hf + 2], z);
; #pragma unroll
;             for (int e = 0; e < 8; ++e) { const float y = (f[e] + bb[e]) * silu_f(z[e]); g[8 * hf + e] = y; ss += y * y; }
;         }
;         ss += __shfl_xor(ss, 1); ss += __shfl_xor(ss, 2); ss += __shfl_xor(ss, 4); ss += __shfl_xor(ss, 8); ss += __shfl_xor(ss, 16);
;         const float r = rsqrtf(ss * (1.f / 512.f) + EPS);
;         float o0[8], o1[8];
; #pragma unroll
;         for (int e = 0; e < 8; ++e) { o0[e] = g[e] * r; o1[e] = g[8 + e] * r; }
;         wt16(Y + (size_t)row * 2048 + c0, pack8(o0)); wt16(Y + (size_t)row * 2048 + c0 + 8, pack8(o1));
;     };
	s_waitcnt vmcnt(14)
	v_lshlrev_b32_e32 v96, 16, v48
	v_and_b32_e32 v97, 0xffff0000, v48
	v_lshlrev_b32_e32 v98, 16, v49
	v_and_b32_e32 v99, 0xffff0000, v49
	v_lshlrev_b32_e32 v100, 16, v50
	v_and_b32_e32 v101, 0xffff0000, v50
	v_lshlrev_b32_e32 v102, 16, v51
	v_and_b32_e32 v103, 0xffff0000, v51
	v_mul_f32_e32 v104, 0xbfb8aa3b, v96
	v_mul_f32_e32 v105, 0xbfb8aa3b, v97
	v_mul_f32_e32 v106, 0xbfb8aa3b, v98
	v_mul_f32_e32 v107, 0xbfb8aa3b, v99
	v_mul_f32_e32 v108, 0xbfb8aa3b, v100
	v_mul_f32_e32 v109, 0xbfb8aa3b, v101
	v_mul_f32_e32 v110, 0xbfb8aa3b, v102
	v_mul_f32_e32 v111, 0xbfb8aa3b, v103
	v_exp_f32_e32 v104, v104
	v_exp_f32_e32 v105, v105
	v_exp_f32_e32 v106, v106
	v_exp_f32_e32 v107, v107
	v_exp_f32_e32 v108, v108
	v_exp_f32_e32 v109, v109
	v_exp_f32_e32 v110, v110
	v_exp_f32_e32 v111, v111
	v_lshlrev_b32_e32 v112, 16, v32
	v_and_b32_e32 v113, 0xffff0000, v32
	v_lshlrev_b32_e32 v114, 16, v33
	v_and_b32_e32 v115, 0xffff0000, v33
	v_lshlrev_b32_e32 v116, 16, v34
	v_and_b32_e32 v117, 0xffff0000, v34
	v_lshlrev_b32_e32 v118, 16, v35
	v_and_b32_e32 v119, 0xffff0000, v35
	v_lshlrev_b32_e32 v120, 16, v40
	v_and_b32_e32 v121, 0xffff0000, v40
	v_lshlrev_b32_e32 v122, 16, v41
	v_and_b32_e32 v123, 0xffff0000, v41
	v_lshlrev_b32_e32 v124, 16, v42
	v_and_b32_e32 v125, 0xffff0000, v42
	v_lshlrev_b32_e32 v126, 16, v43
	v_and_b32_e32 v127, 0xffff0000, v43
	v_add_f32_e32 v112, v112, v120
	v_add_f32_e32 v113, v113, v121
	v_add_f32_e32 v114, v114, v122
	v_add_f32_e32 v115, v115, v123
	v_add_f32_e32 v116, v116, v124
	v_add_f32_e32 v117, v117, v125
	v_add_f32_e32 v118, v118, v126
	v_add_f32_e32 v119, v119, v127
	v_add_f32_e32 v104, 1.0, v104
	v_add_f32_e32 v105, 1.0, v105
	v_add_f32_e32 v106, 1.0, v106
	v_add_f32_e32 v107, 1.0, v107
	v_add_f32_e32 v108, 1.0, v108
	v_add_f32_e32 v109, 1.0, v109
	v_add_f32_e32 v110, 1.0, v110
	v_add_f32_e32 v111, 1.0, v111
	v_rcp_f32_e32 v104, v104
	v_rcp_f32_e32 v105, v105
	v_rcp_f32_e32 v106, v106
	v_rcp_f32_e32 v107, v107
	v_rcp_f32_e32 v108, v108
	v_rcp_f32_e32 v109, v109
	v_rcp_f32_e32 v110, v110
	v_rcp_f32_e32 v111, v111
	v_mul_f32_e32 v96, v96, v104
	v_mul_f32_e32 v97, v97, v105
	v_mul_f32_e32 v98, v98, v106
	v_mul_f32_e32 v99, v99, v107
	v_mul_f32_e32 v100, v100, v108
	v_mul_f32_e32 v101, v101, v109
	v_mul_f32_e32 v102, v102, v110
	v_mul_f32_e32 v103, v103, v111
	v_mul_f32_e32 v80, v112, v96
	v_mul_f32_e32 v81, v113, v97
	v_mul_f32_e32 v82, v114, v98
	v_mul_f32_e32 v83, v115, v99
	v_mul_f32_e32 v84, v116, v100
	v_mul_f32_e32 v85, v117, v101
	v_mul_f32_e32 v86, v118, v102
	v_mul_f32_e32 v87, v119, v103
	v_mul_f32_e32 v128, v80, v80
	v_fmac_f32_e32 v128, v81, v81
	v_fmac_f32_e32 v128, v82, v82
	v_fmac_f32_e32 v128, v83, v83
	v_fmac_f32_e32 v128, v84, v84
	v_fmac_f32_e32 v128, v85, v85
	v_fmac_f32_e32 v128, v86, v86
	v_fmac_f32_e32 v128, v87, v87
	v_lshlrev_b32_e32 v96, 16, v52
	v_and_b32_e32 v97, 0xffff0000, v52
	v_lshlrev_b32_e32 v98, 16, v53
	v_and_b32_e32 v99, 0xffff0000, v53
	v_lshlrev_b32_e32 v100, 16, v54
	v_and_b32_e32 v101, 0xffff0000, v54
	v_lshlrev_b32_e32 v102, 16, v55
	v_and_b32_e32 v103, 0xffff0000, v55
	v_mul_f32_e32 v104, 0xbfb8aa3b, v96
	v_mul_f32_e32 v105, 0xbfb8aa3b, v97
	v_mul_f32_e32 v106, 0xbfb8aa3b, v98
	v_mul_f32_e32 v107, 0xbfb8aa3b, v99
	v_mul_f32_e32 v108, 0xbfb8aa3b, v100
	v_mul_f32_e32 v109, 0xbfb8aa3b, v101
	v_mul_f32_e32 v110, 0xbfb8aa3b, v102
	v_mul_f32_e32 v111, 0xbfb8aa3b, v103
	v_exp_f32_e32 v104, v104
	v_exp_f32_e32 v105, v105
	v_exp_f32_e32 v106, v106
	v_exp_f32_e32 v107, v107
	v_exp_f32_e32 v108, v108
	v_exp_f32_e32 v109, v109
	v_exp_f32_e32 v110, v110
	v_exp_f32_e32 v111, v111
	v_lshlrev_b32_e32 v112, 16, v36
	v_and_b32_e32 v113, 0xffff0000, v36
	v_lshlrev_b32_e32 v114, 16, v37
	v_and_b32_e32 v115, 0xffff0000, v37
	v_lshlrev_b32_e32 v116, 16, v38
	v_and_b32_e32 v117, 0xffff0000, v38
	v_lshlrev_b32_e32 v118, 16, v39
	v_and_b32_e32 v119, 0xffff0000, v39
	v_lshlrev_b32_e32 v120, 16, v44
	v_and_b32_e32 v121, 0xffff0000, v44
	v_lshlrev_b32_e32 v122, 16, v45
	v_and_b32_e32 v123, 0xffff0000, v45
	v_lshlrev_b32_e32 v124, 16, v46
	v_and_b32_e32 v125, 0xffff0000, v46
	v_lshlrev_b32_e32 v126, 16, v47
	v_and_b32_e32 v127, 0xffff0000, v47
	v_add_f32_e32 v112, v112, v120
	v_add_f32_e32 v113, v113, v121
	v_add_f32_e32 v114, v114, v122
	v_add_f32_e32 v115, v115, v123
	v_add_f32_e32 v116, v116, v124
	v_add_f32_e32 v117, v117, v125
	v_add_f32_e32 v118, v118, v126
	v_add_f32_e32 v119, v119, v127
	v_add_f32_e32 v104, 1.0, v104
	v_add_f32_e32 v105, 1.0, v105
	v_add_f32_e32 v106, 1.0, v106
	v_add_f32_e32 v107, 1.0, v107
	v_add_f32_e32 v108, 1.0, v108
	v_add_f32_e32 v109, 1.0, v109
	v_add_f32_e32 v110, 1.0, v110
	v_add_f32_e32 v111, 1.0, v111
	v_rcp_f32_e32 v104, v104
	v_rcp_f32_e32 v105, v105
	v_rcp_f32_e32 v106, v106
	v_rcp_f32_e32 v107, v107
	v_rcp_f32_e32 v108, v108
	v_rcp_f32_e32 v109, v109
	v_rcp_f32_e32 v110, v110
	v_rcp_f32_e32 v111, v111
	v_mul_f32_e32 v96, v96, v104
	v_mul_f32_e32 v97, v97, v105
	v_mul_f32_e32 v98, v98, v106
	v_mul_f32_e32 v99, v99, v107
	v_mul_f32_e32 v100, v100, v108
	v_mul_f32_e32 v101, v101, v109
	v_mul_f32_e32 v102, v102, v110
	v_mul_f32_e32 v103, v103, v111
	v_mul_f32_e32 v88, v112, v96
	v_mul_f32_e32 v89, v113, v97
	v_mul_f32_e32 v90, v114, v98
	v_mul_f32_e32 v91, v115, v99
	v_mul_f32_e32 v92, v116, v100
	v_mul_f32_e32 v93, v117, v101
	v_mul_f32_e32 v94, v118, v102
	v_mul_f32_e32 v95, v119, v103
	v_mul_f32_e32 v129, v88, v88
	v_fmac_f32_e32 v129, v89, v89
	v_fmac_f32_e32 v129, v90, v90
	v_fmac_f32_e32 v129, v91, v91
	v_fmac_f32_e32 v129, v92, v92
	v_fmac_f32_e32 v129, v93, v93
	v_fmac_f32_e32 v129, v94, v94
	v_fmac_f32_e32 v129, v95, v95
	s_nop 1
; #define wt16(p, v) wt16b(WSB, (p), (v))
; __device__ __forceinline__ u32x4 pack8(const float (&f)[8]) { u32x4 v; v.x = cvt_pk_bf16(f[0], f[1]); v.y = cvt_pk_bf16(f[2], f[3]); v.z = cvt_pk_bf16(f[4], f[5]); v.w = cvt_pk_bf16(f[6], f[7]); return v; }
; __device__ __forceinline__ float silu_f(float x) { return x * __builtin_amdgcn_rcpf(1.f + __expf(-x)); }
; __device__ __forceinline__ void ssd_combine_rows(CArgs a, int G) {
;     ...
;     auto finish = [&](int row, const u32x4 (&raw)[6]) {
;         float g[16]; float ss = 0.f;
; #pragma unroll
;         for (int hf = 0; hf < 2; ++hf) {
;             float f[8], bb[8], z[8];
;             unpack8(raw[3 * hf], f); unpack8(raw[3 * hf + 1], bb); unpack8(raw[3 * hf + 2], z);
; #pragma unroll
;             for (int e = 0; e < 8; ++e) { const float y = (f[e] + bb[e]) * silu_f(z[e]); g[8 * hf + e] = y; ss += y * y; }
;         }
;         ss += __shfl_xor(ss, 1); ss += __shfl_xor(ss, 2); ss += __shfl_xor(ss, 4); ss += __shfl_xor(ss, 8); ss += __shfl_xor(ss, 16);
;         const float r = rsqrtf(ss * (1.f / 512.f) + EPS);
;         float o0[8], o1[8];
; #pragma unroll
;         for (int e = 0; e < 8; ++e) { o0[e] = g[e] * r; o1[e] = g[8 + e] * r; }
;         wt16(Y + (size_t)row * 2048 + c0, pack8(o0)); wt16(Y + (size_t)row * 2048 + c0 + 8, pack8(o1));
;     };
;     for (int row = gw; row < T; row += 2 * NGW) {
;         const int row2 = row + NGW;
;         u32x4 ra[6], rb[6];
;         load(row, ra);
;         if (row2 < T) load(row2, rb);
;         finish(row, ra);
;         if (row2 < T) finish(row2, rb);
	v_add_f32_dpp v128, v128, v128 row_shr:1 row_mask:0xf bank_mask:0xf bound_ctrl:0
	v_add_f32_dpp v129, v129, v129 row_shr:1 row_mask:0xf bank_mask:0xf bound_ctrl:0
	s_nop 0
	v_add_f32_dpp v128, v128, v128 row_shr:2 row_mask:0xf bank_mask:0xf bound_ctrl:0
	v_add_f32_dpp v129, v129, v129 row_shr:2 row_mask:0xf bank_mask:0xf bound_ctrl:0
	s_nop 0
	v_add_f32_dpp v128, v128, v128 row_shr:4 row_mask:0xf bank_mask:0xf bound_ctrl:0
	v_add_f32_dpp v129, v129, v129 row_shr:4 row_mask:0xf bank_mask:0xf bound_ctrl:0
	s_nop 0
	v_add_f32_dpp v128, v128, v128 row_shr:8 row_mask:0xf bank_mask:0xf bound_ctrl:0
	v_add_f32_dpp v129, v129, v129 row_shr:8 row_mask:0xf bank_mask:0xf bound_ctrl:0
	s_nop 0
	v_add_f32_dpp v128, v128, v128 row_bcast:15 row_mask:0xa bank_mask:0xf
	v_add_f32_dpp v129, v129, v129 row_bcast:15 row_mask:0xa bank_mask:0xf
	s_nop 0
	v_add_f32_dpp v128, v128, v128 row_bcast:31 row_mask:0xc bank_mask:0xf
	v_add_f32_dpp v129, v129, v129 row_bcast:31 row_mask:0xc bank_mask:0xf
	s_nop 0
	s_nop 0
	v_readlane_b32 s20, v128, 63
	v_readlane_b32 s21, v129, 63
	s_nop 1
	v_mov_b32_e32 v130, s20
	v_mov_b32_e32 v131, s21
	v_fmamk_f32 v130, v130, 0x3b000000, v245
	v_fmamk_f32 v131, v131, 0x3b000000, v245
	v_rsq_f32_e32 v130, v130
	v_rsq_f32_e32 v131, v131
	s_nop 0
	v_mul_f32_e32 v80, v80, v130
	v_mul_f32_e32 v81, v81, v130
	v_mul_f32_e32 v82, v82, v130
	v_mul_f32_e32 v83, v83, v130
	v_mul_f32_e32 v84, v84, v130
	v_mul_f32_e32 v85, v85, v130
	v_mul_f32_e32 v86, v86, v130
	v_mul_f32_e32 v87, v87, v130
	v_cvt_pk_bf16_f32 v80, v80, v81
	v_cvt_pk_bf16_f32 v81, v82, v83
	v_cvt_pk_bf16_f32 v82, v84, v85
	v_cvt_pk_bf16_f32 v83, v86, v87
	v_mul_f32_e32 v88, v88, v131
	v_mul_f32_e32 v89, v89, v131
	v_mul_f32_e32 v90, v90, v131
	v_mul_f32_e32 v91, v91, v131
	v_mul_f32_e32 v92, v92, v131
	v_mul_f32_e32 v93, v93, v131
	v_mul_f32_e32 v94, v94, v131
	v_mul_f32_e32 v95, v95, v131
	v_cvt_pk_bf16_f32 v88, v88, v89
	v_cvt_pk_bf16_f32 v89, v90, v91
	v_cvt_pk_bf16_f32 v90, v92, v93
	v_cvt_pk_bf16_f32 v91, v94, v95
	s_lshl_b32 s19, s10, 12
	s_add_u32 s19, s19, 0x10a00000
	buffer_store_dwordx4 v[80:83], v2, s[60:63], s19 offen sc1
	buffer_store_dwordx4 v[88:91], v2, s[60:63], s19 offen offset:1024 sc1
	s_mul_i32 s12, s11, 3
	s_add_i32 s12, s10, s12
	s_cmp_lt_u32 s12, 0x4000
	s_cselect_b32 s12, s12, s10
	s_lshl_b32 s16, s12, 12
	s_add_u32 s16, s16, 0x10a00000
	s_lshl_b32 s17, s12, 11
	s_add_u32 s17, s17, 0x18a00000
	s_mul_i32 s18, s12, 0x2400
	s_add_u32 s18, s18, 0x3a00000
	buffer_load_dwordx4 v[32:35], v2, s[60:63], s16 offen
	buffer_load_dwordx4 v[36:39], v2, s[60:63], s16 offen offset:1024
	buffer_load_dwordx4 v[40:43], v2, s[60:63], s17 offen
	buffer_load_dwordx4 v[44:47], v2, s[60:63], s17 offen offset:1024
	buffer_load_dwordx4 v[48:51], v2, s[60:63], s18 offen
	buffer_load_dwordx4 v[52:55], v2, s[60:63], s18 offen offset:1024
	s_add_i32 s10, s10, s11
	s_cmp_lt_u32 s10, 0x4000
	s_cbranch_scc0 .Lcmb_done
	s_waitcnt vmcnt(16)
	v_lshlrev_b32_e32 v96, 16, v72
	v_and_b32_e32 v97, 0xffff0000, v72
	v_lshlrev_b32_e32 v98, 16, v73
	v_and_b32_e32 v99, 0xffff0000, v73
	v_lshlrev_b32_e32 v100, 16, v74
	v_and_b32_e32 v101, 0xffff0000, v74
	v_lshlrev_b32_e32 v102, 16, v75
	v_and_b32_e32 v103, 0xffff0000, v75
	v_mul_f32_e32 v104, 0xbfb8aa3b, v96
	v_mul_f32_e32 v105, 0xbfb8aa3b, v97
	v_mul_f32_e32 v106, 0xbfb8aa3b, v98
	v_mul_f32_e32 v107, 0xbfb8aa3b, v99
	v_mul_f32_e32 v108, 0xbfb8aa3b, v100
	v_mul_f32_e32 v109, 0xbfb8aa3b, v101
	v_mul_f32_e32 v110, 0xbfb8aa3b, v102
	v_mul_f32_e32 v111, 0xbfb8aa3b, v103
	v_exp_f32_e32 v104, v104
	v_exp_f32_e32 v105, v105
	v_exp_f32_e32 v106, v106
	v_exp_f32_e32 v107, v107
	v_exp_f32_e32 v108, v108
	v_exp_f32_e32 v109, v109
	v_exp_f32_e32 v110, v110
	v_exp_f32_e32 v111, v111
	v_lshlrev_b32_e32 v112, 16, v56
	v_and_b32_e32 v113, 0xffff0000, v56
	v_lshlrev_b32_e32 v114, 16, v57
	v_and_b32_e32 v115, 0xffff0000, v57
	v_lshlrev_b32_e32 v116, 16, v58
	v_and_b32_e32 v117, 0xffff0000, v58
	v_lshlrev_b32_e32 v118, 16, v59
	v_and_b32_e32 v119, 0xffff0000, v59
	v_lshlrev_b32_e32 v120, 16, v64
	v_and_b32_e32 v121, 0xffff0000, v64
	v_lshlrev_b32_e32 v122, 16, v65
	v_and_b32_e32 v123, 0xffff0000, v65
	v_lshlrev_b32_e32 v124, 16, v66
	v_and_b32_e32 v125, 0xffff0000, v66
	v_lshlrev_b32_e32 v126, 16, v67
	v_and_b32_e32 v127, 0xffff0000, v67
	v_add_f32_e32 v112, v112, v120
	v_add_f32_e32 v113, v113, v121
	v_add_f32_e32 v114, v114, v122
	v_add_f32_e32 v115, v115, v123
	v_add_f32_e32 v116, v116, v124
	v_add_f32_e32 v117, v117, v125
	v_add_f32_e32 v118, v118, v126
	v_add_f32_e32 v119, v119, v127
	v_add_f32_e32 v104, 1.0, v104
	v_add_f32_e32 v105, 1.0, v105
	v_add_f32_e32 v106, 1.0, v106
	v_add_f32_e32 v107, 1.0, v107
	v_add_f32_e32 v108, 1.0, v108
	v_add_f32_e32 v109, 1.0, v109
	v_add_f32_e32 v110, 1.0, v110
	v_add_f32_e32 v111, 1.0, v111
	v_rcp_f32_e32 v104, v104
	v_rcp_f32_e32 v105, v105
	v_rcp_f32_e32 v106, v106
	v_rcp_f32_e32 v107, v107
	v_rcp_f32_e32 v108, v108
	v_rcp_f32_e32 v109, v109
	v_rcp_f32_e32 v110, v110
	v_rcp_f32_e32 v111, v111
	v_mul_f32_e32 v96, v96, v104
	v_mul_f32_e32 v97, v97, v105
	v_mul_f32_e32 v98, v98, v106
	v_mul_f32_e32 v99, v99, v107
	v_mul_f32_e32 v100, v100, v108
	v_mul_f32_e32 v101, v101, v109
	v_mul_f32_e32 v102, v102, v110
	v_mul_f32_e32 v103, v103, v111
	v_mul_f32_e32 v80, v112, v96
	v_mul_f32_e32 v81, v113, v97
	v_mul_f32_e32 v82, v114, v98
	v_mul_f32_e32 v83, v115, v99
	v_mul_f32_e32 v84, v116, v100
	v_mul_f32_e32 v85, v117, v101
	v_mul_f32_e32 v86, v118, v102
	v_mul_f32_e32 v87, v119, v103
	v_mul_f32_e32 v128, v80, v80
	v_fmac_f32_e32 v128, v81, v81
	v_fmac_f32_e32 v128, v82, v82
	v_fmac_f32_e32 v128, v83, v83
	v_fmac_f32_e32 v128, v84, v84
; #define wt16(p, v) wt16b(WSB, (p), (v))
; __device__ __forceinline__ u32x4 pack8(const float (&f)[8]) { u32x4 v; v.x = cvt_pk_bf16(f[0], f[1]); v.y = cvt_pk_bf16(f[2], f[3]); v.z = cvt_pk_bf16(f[4], f[5]); v.w = cvt_pk_bf16(f[6], f[7]); return v; }
; __device__ __forceinline__ float silu_f(float x) { return x * __builtin_amdgcn_rcpf(1.f + __expf(-x)); }
; __device__ __forceinline__ void ssd_combine_rows(CArgs a, int G) {
;     ...
;     auto finish = [&](int row, const u32x4 (&raw)[6]) {
;         float g[16]; float ss = 0.f;
; #pragma unroll
;         for (int hf = 0; hf < 2; ++hf) {
;             float f[8], bb[8], z[8];
;             unpack8(raw[3 * hf], f); unpack8(raw[3 * hf + 1], bb); unpack8(raw[3 * hf + 2], z);
; #pragma unroll
;             for (int e = 0; e < 8; ++e) { const float y = (f[e] + bb[e]) * silu_f(z[e]); g[8 * hf + e] = y; ss += y * y; }
;         }
;         ss += __shfl_xor(ss, 1); ss += __shfl_xor(ss, 2); ss += __shfl_xor(ss, 4); ss += __shfl_xor(ss, 8); ss += __shfl_xor(ss, 16);
;         const float r = rsqrtf(ss * (1.f / 512.f) + EPS);
;         float o0[8], o1[8];
; #pragma unroll
;         for (int e = 0; e < 8; ++e) { o0[e] = g[e] * r; o1[e] = g[8 + e] * r; }
;         wt16(Y + (size_t)row * 2048 + c0, pack8(o0)); wt16(Y + (size_t)row * 2048 + c0 + 8, pack8(o1));
;     };
;     for (int row = gw; row < T; row += 2 * NGW) {
;         const int row2 = row + NGW;
;         u32x4 ra[6], rb[6];
;         load(row, ra);
;         if (row2 < T) load(row2, rb);
;         finish(row, ra);
;         if (row2 < T) finish(row2, rb);
	v_fmac_f32_e32 v128, v85, v85
	v_fmac_f32_e32 v128, v86, v86
	v_fmac_f32_e32 v128, v87, v87
	v_lshlrev_b32_e32 v96, 16, v76
	v_and_b32_e32 v97, 0xffff0000, v76
	v_lshlrev_b32_e32 v98, 16, v77
	v_and_b32_e32 v99, 0xffff0000, v77
	v_lshlrev_b32_e32 v100, 16, v78
	v_and_b32_e32 v101, 0xffff0000, v78
	v_lshlrev_b32_e32 v102, 16, v79
	v_and_b32_e32 v103, 0xffff0000, v79
	v_mul_f32_e32 v104, 0xbfb8aa3b, v96
	v_mul_f32_e32 v105, 0xbfb8aa3b, v97
	v_mul_f32_e32 v106, 0xbfb8aa3b, v98
	v_mul_f32_e32 v107, 0xbfb8aa3b, v99
	v_mul_f32_e32 v108, 0xbfb8aa3b, v100
	v_mul_f32_e32 v109, 0xbfb8aa3b, v101
	v_mul_f32_e32 v110, 0xbfb8aa3b, v102
	v_mul_f32_e32 v111, 0xbfb8aa3b, v103
	v_exp_f32_e32 v104, v104
	v_exp_f32_e32 v105, v105
	v_exp_f32_e32 v106, v106
	v_exp_f32_e32 v107, v107
	v_exp_f32_e32 v108, v108
	v_exp_f32_e32 v109, v109
	v_exp_f32_e32 v110, v110
	v_exp_f32_e32 v111, v111
	v_lshlrev_b32_e32 v112, 16, v60
	v_and_b32_e32 v113, 0xffff0000, v60
	v_lshlrev_b32_e32 v114, 16, v61
	v_and_b32_e32 v115, 0xffff0000, v61
	v_lshlrev_b32_e32 v116, 16, v62
	v_and_b32_e32 v117, 0xffff0000, v62
	v_lshlrev_b32_e32 v118, 16, v63
	v_and_b32_e32 v119, 0xffff0000, v63
	v_lshlrev_b32_e32 v120, 16, v68
	v_and_b32_e32 v121, 0xffff0000, v68
	v_lshlrev_b32_e32 v122, 16, v69
	v_and_b32_e32 v123, 0xffff0000, v69
	v_lshlrev_b32_e32 v124, 16, v70
	v_and_b32_e32 v125, 0xffff0000, v70
	v_lshlrev_b32_e32 v126, 16, v71
	v_and_b32_e32 v127, 0xffff0000, v71
	v_add_f32_e32 v112, v112, v120
	v_add_f32_e32 v113, v113, v121
	v_add_f32_e32 v114, v114, v122
	v_add_f32_e32 v115, v115, v123
	v_add_f32_e32 v116, v116, v124
	v_add_f32_e32 v117, v117, v125
	v_add_f32_e32 v118, v118, v126
	v_add_f32_e32 v119, v119, v127
	v_add_f32_e32 v104, 1.0, v104
	v_add_f32_e32 v105, 1.0, v105
	v_add_f32_e32 v106, 1.0, v106
	v_add_f32_e32 v107, 1.0, v107
	v_add_f32_e32 v108, 1.0, v108
	v_add_f32_e32 v109, 1.0, v109
	v_add_f32_e32 v110, 1.0, v110
	v_add_f32_e32 v111, 1.0, v111
	v_rcp_f32_e32 v104, v104
	v_rcp_f32_e32 v105, v105
	v_rcp_f32_e32 v106, v106
	v_rcp_f32_e32 v107, v107
	v_rcp_f32_e32 v108, v108
	v_rcp_f32_e32 v109, v109
	v_rcp_f32_e32 v110, v110
	v_rcp_f32_e32 v111, v111
	v_mul_f32_e32 v96, v96, v104
	v_mul_f32_e32 v97, v97, v105
	v_mul_f32_e32 v98, v98, v106
	v_mul_f32_e32 v99, v99, v107
	v_mul_f32_e32 v100, v100, v108
	v_mul_f32_e32 v101, v101, v109
	v_mul_f32_e32 v102, v102, v110
	v_mul_f32_e32 v103, v103, v111
	v_mul_f32_e32 v88, v112, v96
	v_mul_f32_e32 v89, v113, v97
	v_mul_f32_e32 v90, v114, v98
	v_mul_f32_e32 v91, v115, v99
	v_mul_f32_e32 v92, v116, v100
	v_mul_f32_e32 v93, v117, v101
	v_mul_f32_e32 v94, v118, v102
	v_mul_f32_e32 v95, v119, v103
	v_mul_f32_e32 v129, v88, v88
	v_fmac_f32_e32 v129, v89, v89
	v_fmac_f32_e32 v129, v90, v90
	v_fmac_f32_e32 v129, v91, v91
	v_fmac_f32_e32 v129, v92, v92
	v_fmac_f32_e32 v129, v93, v93
	v_fmac_f32_e32 v129, v94, v94
	v_fmac_f32_e32 v129, v95, v95
	s_nop 1
	v_add_f32_dpp v128, v128, v128 row_shr:1 row_mask:0xf bank_mask:0xf bound_ctrl:0
	v_add_f32_dpp v129, v129, v129 row_shr:1 row_mask:0xf bank_mask:0xf bound_ctrl:0
	s_nop 0
	v_add_f32_dpp v128, v128, v128 row_shr:2 row_mask:0xf bank_mask:0xf bound_ctrl:0
	v_add_f32_dpp v129, v129, v129 row_shr:2 row_mask:0xf bank_mask:0xf bound_ctrl:0
	s_nop 0
	v_add_f32_dpp v128, v128, v128 row_shr:4 row_mask:0xf bank_mask:0xf bound_ctrl:0
	v_add_f32_dpp v129, v129, v129 row_shr:4 row_mask:0xf bank_mask:0xf bound_ctrl:0
	s_nop 0
	v_add_f32_dpp v128, v128, v128 row_shr:8 row_mask:0xf bank_mask:0xf bound_ctrl:0
	v_add_f32_dpp v129, v129, v129 row_shr:8 row_mask:0xf bank_mask:0xf bound_ctrl:0
	s_nop 0
	v_add_f32_dpp v128, v128, v128 row_bcast:15 row_mask:0xa bank_mask:0xf
	v_add_f32_dpp v129, v129, v129 row_bcast:15 row_mask:0xa bank_mask:0xf
	s_nop 0
	v_add_f32_dpp v128, v128, v128 row_bcast:31 row_mask:0xc bank_mask:0xf
	v_add_f32_dpp v129, v129, v129 row_bcast:31 row_mask:0xc bank_mask:0xf
	s_nop 0
	s_nop 0
	v_readlane_b32 s20, v128, 63
	v_readlane_b32 s21, v129, 63
	s_nop 1
	v_mov_b32_e32 v130, s20
	v_mov_b32_e32 v131, s21
	v_fmamk_f32 v130, v130, 0x3b000000, v245
	v_fmamk_f32 v131, v131, 0x3b000000, v245
	v_rsq_f32_e32 v130, v130
	v_rsq_f32_e32 v131, v131
	s_nop 0
	v_mul_f32_e32 v80, v80, v130
	v_mul_f32_e32 v81, v81, v130
	v_mul_f32_e32 v82, v82, v130
	v_mul_f32_e32 v83, v83, v130
	v_mul_f32_e32 v84, v84, v130
	v_mul_f32_e32 v85, v85, v130
	v_mul_f32_e32 v86, v86, v130
	v_mul_f32_e32 v87, v87, v130
	v_cvt_pk_bf16_f32 v80, v80, v81
	v_cvt_pk_bf16_f32 v81, v82, v83
	v_cvt_pk_bf16_f32 v82, v84, v85
	v_cvt_pk_bf16_f32 v83, v86, v87
	v_mul_f32_e32 v88, v88, v131
	v_mul_f32_e32 v89, v89, v131
	v_mul_f32_e32 v90, v90, v131
	v_mul_f32_e32 v91, v91, v131
	v_mul_f32_e32 v92, v92, v131
	v_mul_f32_e32 v93, v93, v131
	v_mul_f32_e32 v94, v94, v131
	v_mul_f32_e32 v95, v95, v131
	v_cvt_pk_bf16_f32 v88, v88, v89
	v_cvt_pk_bf16_f32 v89, v90, v91
	v_cvt_pk_bf16_f32 v90, v92, v93
	v_cvt_pk_bf16_f32 v91, v94, v95
	s_lshl_b32 s19, s10, 12
	s_add_u32 s19, s19, 0x10a00000
	buffer_store_dwordx4 v[80:83], v2, s[60:63], s19 offen sc1
	buffer_store_dwordx4 v[88:91], v2, s[60:63], s19 offen offset:1024 sc1
	s_mul_i32 s12, s11, 3
	s_add_i32 s12, s10, s12
	s_cmp_lt_u32 s12, 0x4000
	s_cselect_b32 s12, s12, s10
	s_lshl_b32 s16, s12, 12
	s_add_u32 s16, s16, 0x10a00000
	s_lshl_b32 s17, s12, 11
	s_add_u32 s17, s17, 0x18a00000
	s_mul_i32 s18, s12, 0x2400
	s_add_u32 s18, s18, 0x3a00000
	buffer_load_dwordx4 v[56:59], v2, s[60:63], s16 offen
	buffer_load_dwordx4 v[60:63], v2, s[60:63], s16 offen offset:1024
	buffer_load_dwordx4 v[64:67], v2, s[60:63], s17 offen
	buffer_load_dwordx4 v[68:71], v2, s[60:63], s17 offen offset:1024
	buffer_load_dwordx4 v[72:75], v2, s[60:63], s18 offen
	buffer_load_dwordx4 v[76:79], v2, s[60:63], s18 offen offset:1024
	s_add_i32 s10, s10, s11
	s_cmp_lt_u32 s10, 0x4000
	s_cbranch_scc0 .Lcmb_done
; __device__ __forceinline__ float silu_f(float x) { return x * __builtin_amdgcn_rcpf(1.f + __expf(-x)); }
; __device__ __forceinline__ void ssd_combine_rows(CArgs a, int G) {
;     ...
;     auto finish = [&](int row, const u32x4 (&raw)[6]) {
;         float g[16]; float ss = 0.f;
; #pragma unroll
;         for (int hf = 0; hf < 2; ++hf) {
;             float f[8], bb[8], z[8];
;             unpack8(raw[3 * hf], f); unpack8(raw[3 * hf + 1], bb); unpack8(raw[3 * hf + 2], z);
; #pragma unroll
;             for (int e = 0; e < 8; ++e) { const float y = (f[e] + bb[e]) * silu_f(z[e]); g[8 * hf + e] = y; ss += y * y; }
;         }
.Lcmb_loop:
	s_waitcnt vmcnt(16)
	v_lshlrev_b32_e32 v96, 16, v24
	v_and_b32_e32 v97, 0xffff0000, v24
	v_lshlrev_b32_e32 v98, 16, v25
	v_and_b32_e32 v99, 0xffff0000, v25
	v_lshlrev_b32_e32 v100, 16, v26
	v_and_b32_e32 v101, 0xffff0000, v26
	v_lshlrev_b32_e32 v102, 16, v27
	v_and_b32_e32 v103, 0xffff0000, v27
	v_mul_f32_e32 v104, 0xbfb8aa3b, v96
	v_mul_f32_e32 v105, 0xbfb8aa3b, v97
	v_mul_f32_e32 v106, 0xbfb8aa3b, v98
	v_mul_f32_e32 v107, 0xbfb8aa3b, v99
	v_mul_f32_e32 v108, 0xbfb8aa3b, v100
	v_mul_f32_e32 v109, 0xbfb8aa3b, v101
	v_mul_f32_e32 v110, 0xbfb8aa3b, v102
	v_mul_f32_e32 v111, 0xbfb8aa3b, v103
	v_exp_f32_e32 v104, v104
	v_exp_f32_e32 v105, v105
	v_exp_f32_e32 v106, v106
	v_exp_f32_e32 v107, v107
	v_exp_f32_e32 v108, v108
	v_exp_f32_e32 v109, v109
	v_exp_f32_e32 v110, v110
	v_exp_f32_e32 v111, v111
	v_lshlrev_b32_e32 v112, 16, v8
	v_and_b32_e32 v113, 0xffff0000, v8
	v_lshlrev_b32_e32 v114, 16, v9
	v_and_b32_e32 v115, 0xffff0000, v9
	v_lshlrev_b32_e32 v116, 16, v10
	v_and_b32_e32 v117, 0xffff0000, v10
	v_lshlrev_b32_e32 v118, 16, v11
	v_and_b32_e32 v119, 0xffff0000, v11
	v_lshlrev_b32_e32 v120, 16, v16
	v_and_b32_e32 v121, 0xffff0000, v16
	v_lshlrev_b32_e32 v122, 16, v17
	v_and_b32_e32 v123, 0xffff0000, v17
	v_lshlrev_b32_e32 v124, 16, v18
	v_and_b32_e32 v125, 0xffff0000, v18
	v_lshlrev_b32_e32 v126, 16, v19
	v_and_b32_e32 v127, 0xffff0000, v19
	v_add_f32_e32 v112, v112, v120
	v_add_f32_e32 v113, v113, v121
	v_add_f32_e32 v114, v114, v122
	v_add_f32_e32 v115, v115, v123
	v_add_f32_e32 v116, v116, v124
	v_add_f32_e32 v117, v117, v125
	v_add_f32_e32 v118, v118, v126
	v_add_f32_e32 v119, v119, v127
	v_add_f32_e32 v104, 1.0, v104
	v_add_f32_e32 v105, 1.0, v105
	v_add_f32_e32 v106, 1.0, v106
	v_add_f32_e32 v107, 1.0, v107
	v_add_f32_e32 v108, 1.0, v108
	v_add_f32_e32 v109, 1.0, v109
	v_add_f32_e32 v110, 1.0, v110
	v_add_f32_e32 v111, 1.0, v111
	v_rcp_f32_e32 v104, v104
	v_rcp_f32_e32 v105, v105
	v_rcp_f32_e32 v106, v106
	v_rcp_f32_e32 v107, v107
	v_rcp_f32_e32 v108, v108
	v_rcp_f32_e32 v109, v109
	v_rcp_f32_e32 v110, v110
	v_rcp_f32_e32 v111, v111
	v_mul_f32_e32 v96, v96, v104
	v_mul_f32_e32 v97, v97, v105
	v_mul_f32_e32 v98, v98, v106
	v_mul_f32_e32 v99, v99, v107
	v_mul_f32_e32 v100, v100, v108
	v_mul_f32_e32 v101, v101, v109
	v_mul_f32_e32 v102, v102, v110
	v_mul_f32_e32 v103, v103, v111
	v_mul_f32_e32 v80, v112, v96
	v_mul_f32_e32 v81, v113, v97
	v_mul_f32_e32 v82, v114, v98
	v_mul_f32_e32 v83, v115, v99
	v_mul_f32_e32 v84, v116, v100
	v_mul_f32_e32 v85, v117, v101
	v_mul_f32_e32 v86, v118, v102
	v_mul_f32_e32 v87, v119, v103
	v_mul_f32_e32 v128, v80, v80
	v_fmac_f32_e32 v128, v81, v81
	v_fmac_f32_e32 v128, v82, v82
	v_fmac_f32_e32 v128, v83, v83
	v_fmac_f32_e32 v128, v84, v84
	v_fmac_f32_e32 v128, v85, v85
	v_fmac_f32_e32 v128, v86, v86
	v_fmac_f32_e32 v128, v87, v87
	v_lshlrev_b32_e32 v96, 16, v28
	v_and_b32_e32 v97, 0xffff0000, v28
	v_lshlrev_b32_e32 v98, 16, v29
	v_and_b32_e32 v99, 0xffff0000, v29
	v_lshlrev_b32_e32 v100, 16, v30
	v_and_b32_e32 v101, 0xffff0000, v30
	v_lshlrev_b32_e32 v102, 16, v31
	v_and_b32_e32 v103, 0xffff0000, v31
	v_mul_f32_e32 v104, 0xbfb8aa3b, v96
	v_mul_f32_e32 v105, 0xbfb8aa3b, v97
	v_mul_f32_e32 v106, 0xbfb8aa3b, v98
	v_mul_f32_e32 v107, 0xbfb8aa3b, v99
	v_mul_f32_e32 v108, 0xbfb8aa3b, v100
	v_mul_f32_e32 v109, 0xbfb8aa3b, v101
	v_mul_f32_e32 v110, 0xbfb8aa3b, v102
	v_mul_f32_e32 v111, 0xbfb8aa3b, v103
	v_exp_f32_e32 v104, v104
	v_exp_f32_e32 v105, v105
	v_exp_f32_e32 v106, v106
	v_exp_f32_e32 v107, v107
	v_exp_f32_e32 v108, v108
	v_exp_f32_e32 v109, v109
	v_exp_f32_e32 v110, v110
	v_exp_f32_e32 v111, v111
	v_lshlrev_b32_e32 v112, 16, v12
	v_and_b32_e32 v113, 0xffff0000, v12
	v_lshlrev_b32_e32 v114, 16, v13
	v_and_b32_e32 v115, 0xffff0000, v13
	v_lshlrev_b32_e32 v116, 16, v14
	v_and_b32_e32 v117, 0xffff0000, v14
	v_lshlrev_b32_e32 v118, 16, v15
	v_and_b32_e32 v119, 0xffff0000, v15
	v_lshlrev_b32_e32 v120, 16, v20
	v_and_b32_e32 v121, 0xffff0000, v20
	v_lshlrev_b32_e32 v122, 16, v21
	v_and_b32_e32 v123, 0xffff0000, v21
	v_lshlrev_b32_e32 v124, 16, v22
	v_and_b32_e32 v125, 0xffff0000, v22
	v_lshlrev_b32_e32 v126, 16, v23
	v_and_b32_e32 v127, 0xffff0000, v23
	v_add_f32_e32 v112, v112, v120
	v_add_f32_e32 v113, v113, v121
	v_add_f32_e32 v114, v114, v122
	v_add_f32_e32 v115, v115, v123
	v_add_f32_e32 v116, v116, v124
	v_add_f32_e32 v117, v117, v125
	v_add_f32_e32 v118, v118, v126
	v_add_f32_e32 v119, v119, v127
	v_add_f32_e32 v104, 1.0, v104
	v_add_f32_e32 v105, 1.0, v105
	v_add_f32_e32 v106, 1.0, v106
	v_add_f32_e32 v107, 1.0, v107
	v_add_f32_e32 v108, 1.0, v108
	v_add_f32_e32 v109, 1.0, v109
	v_add_f32_e32 v110, 1.0, v110
	v_add_f32_e32 v111, 1.0, v111
	v_rcp_f32_e32 v104, v104
	v_rcp_f32_e32 v105, v105
	v_rcp_f32_e32 v106, v106
	v_rcp_f32_e32 v107, v107
	v_rcp_f32_e32 v108, v108
	v_rcp_f32_e32 v109, v109
	v_rcp_f32_e32 v110, v110
	v_rcp_f32_e32 v111, v111
	v_mul_f32_e32 v96, v96, v104
	v_mul_f32_e32 v97, v97, v105
	v_mul_f32_e32 v98, v98, v106
	v_mul_f32_e32 v99, v99, v107
	v_mul_f32_e32 v100, v100, v108
	v_mul_f32_e32 v101, v101, v109
	v_mul_f32_e32 v102, v102, v110
	v_mul_f32_e32 v103, v103, v111
	v_mul_f32_e32 v88, v112, v96
	v_mul_f32_e32 v89, v113, v97
	v_mul_f32_e32 v90, v114, v98
	v_mul_f32_e32 v91, v115, v99
	v_mul_f32_e32 v92, v116, v100
	v_mul_f32_e32 v93, v117, v101
	v_mul_f32_e32 v94, v118, v102
	v_mul_f32_e32 v95, v119, v103
	v_mul_f32_e32 v129, v88, v88
	v_fmac_f32_e32 v129, v89, v89
	v_fmac_f32_e32 v129, v90, v90
	v_fmac_f32_e32 v129, v91, v91
	v_fmac_f32_e32 v129, v92, v92
	v_fmac_f32_e32 v129, v93, v93
	v_fmac_f32_e32 v129, v94, v94
	v_fmac_f32_e32 v129, v95, v95
	s_nop 1
; #define wt16(p, v) wt16b(WSB, (p), (v))
; __device__ __forceinline__ u32x4 pack8(const float (&f)[8]) { u32x4 v; v.x = cvt_pk_bf16(f[0], f[1]); v.y = cvt_pk_bf16(f[2], f[3]); v.z = cvt_pk_bf16(f[4], f[5]); v.w = cvt_pk_bf16(f[6], f[7]); return v; }
; __device__ __forceinline__ void ssd_combine_rows(CArgs a, int G) {
;     ...
;         ss += __shfl_xor(ss, 1); ss += __shfl_xor(ss, 2); ss += __shfl_xor(ss, 4); ss += __shfl_xor(ss, 8); ss += __shfl_xor(ss, 16);
;         const float r = rsqrtf(ss * (1.f / 512.f) + EPS);
;         float o0[8], o1[8];
; #pragma unroll
;         for (int e = 0; e < 8; ++e) { o0[e] = g[e] * r; o1[e] = g[8 + e] * r; }
;         wt16(Y + (size_t)row * 2048 + c0, pack8(o0)); wt16(Y + (size_t)row * 2048 + c0 + 8, pack8(o1));
;     };
;     for (int row = gw; row < T; row += 2 * NGW) {
;         const int row2 = row + NGW;
;         u32x4 ra[6], rb[6];
;         load(row, ra);
;         if (row2 < T) load(row2, rb);
;         finish(row, ra);
;         if (row2 < T) finish(row2, rb);
	v_add_f32_dpp v128, v128, v128 row_shr:1 row_mask:0xf bank_mask:0xf bound_ctrl:0
	v_add_f32_dpp v129, v129, v129 row_shr:1 row_mask:0xf bank_mask:0xf bound_ctrl:0
	s_nop 0
	v_add_f32_dpp v128, v128, v128 row_shr:2 row_mask:0xf bank_mask:0xf bound_ctrl:0
	v_add_f32_dpp v129, v129, v129 row_shr:2 row_mask:0xf bank_mask:0xf bound_ctrl:0
	s_nop 0
	v_add_f32_dpp v128, v128, v128 row_shr:4 row_mask:0xf bank_mask:0xf bound_ctrl:0
	v_add_f32_dpp v129, v129, v129 row_shr:4 row_mask:0xf bank_mask:0xf bound_ctrl:0
	s_nop 0
	v_add_f32_dpp v128, v128, v128 row_shr:8 row_mask:0xf bank_mask:0xf bound_ctrl:0
	v_add_f32_dpp v129, v129, v129 row_shr:8 row_mask:0xf bank_mask:0xf bound_ctrl:0
	s_nop 0
	v_add_f32_dpp v128, v128, v128 row_bcast:15 row_mask:0xa bank_mask:0xf
	v_add_f32_dpp v129, v129, v129 row_bcast:15 row_mask:0xa bank_mask:0xf
	s_nop 0
	v_add_f32_dpp v128, v128, v128 row_bcast:31 row_mask:0xc bank_mask:0xf
	v_add_f32_dpp v129, v129, v129 row_bcast:31 row_mask:0xc bank_mask:0xf
	s_nop 0
	s_nop 0
	v_readlane_b32 s20, v128, 63
	v_readlane_b32 s21, v129, 63
	s_nop 1
	v_mov_b32_e32 v130, s20
	v_mov_b32_e32 v131, s21
	v_fmamk_f32 v130, v130, 0x3b000000, v245
	v_fmamk_f32 v131, v131, 0x3b000000, v245
	v_rsq_f32_e32 v130, v130
	v_rsq_f32_e32 v131, v131
	s_nop 0
	v_mul_f32_e32 v80, v80, v130
	v_mul_f32_e32 v81, v81, v130
	v_mul_f32_e32 v82, v82, v130
	v_mul_f32_e32 v83, v83, v130
	v_mul_f32_e32 v84, v84, v130
	v_mul_f32_e32 v85, v85, v130
	v_mul_f32_e32 v86, v86, v130
	v_mul_f32_e32 v87, v87, v130
	v_cvt_pk_bf16_f32 v80, v80, v81
	v_cvt_pk_bf16_f32 v81, v82, v83
	v_cvt_pk_bf16_f32 v82, v84, v85
	v_cvt_pk_bf16_f32 v83, v86, v87
	v_mul_f32_e32 v88, v88, v131
	v_mul_f32_e32 v89, v89, v131
	v_mul_f32_e32 v90, v90, v131
	v_mul_f32_e32 v91, v91, v131
	v_mul_f32_e32 v92, v92, v131
	v_mul_f32_e32 v93, v93, v131
	v_mul_f32_e32 v94, v94, v131
	v_mul_f32_e32 v95, v95, v131
	v_cvt_pk_bf16_f32 v88, v88, v89
	v_cvt_pk_bf16_f32 v89, v90, v91
	v_cvt_pk_bf16_f32 v90, v92, v93
	v_cvt_pk_bf16_f32 v91, v94, v95
	s_lshl_b32 s19, s10, 12
	s_add_u32 s19, s19, 0x10a00000
	buffer_store_dwordx4 v[80:83], v2, s[60:63], s19 offen sc1
	buffer_store_dwordx4 v[88:91], v2, s[60:63], s19 offen offset:1024 sc1
	s_mul_i32 s12, s11, 3
	s_add_i32 s12, s10, s12
	s_cmp_lt_u32 s12, 0x4000
	s_cselect_b32 s12, s12, s10
	s_lshl_b32 s16, s12, 12
	s_add_u32 s16, s16, 0x10a00000
	s_lshl_b32 s17, s12, 11
	s_add_u32 s17, s17, 0x18a00000
	s_mul_i32 s18, s12, 0x2400
	s_add_u32 s18, s18, 0x3a00000
	buffer_load_dwordx4 v[8:11], v2, s[60:63], s16 offen
	buffer_load_dwordx4 v[12:15], v2, s[60:63], s16 offen offset:1024
	buffer_load_dwordx4 v[16:19], v2, s[60:63], s17 offen
	buffer_load_dwordx4 v[20:23], v2, s[60:63], s17 offen offset:1024
	buffer_load_dwordx4 v[24:27], v2, s[60:63], s18 offen
	buffer_load_dwordx4 v[28:31], v2, s[60:63], s18 offen offset:1024
	s_add_i32 s10, s10, s11
	s_cmp_lt_u32 s10, 0x4000
	s_cbranch_scc0 .Lcmb_done
	s_waitcnt vmcnt(16)
	v_lshlrev_b32_e32 v96, 16, v48
	v_and_b32_e32 v97, 0xffff0000, v48
	v_lshlrev_b32_e32 v98, 16, v49
	v_and_b32_e32 v99, 0xffff0000, v49
	v_lshlrev_b32_e32 v100, 16, v50
	v_and_b32_e32 v101, 0xffff0000, v50
	v_lshlrev_b32_e32 v102, 16, v51
	v_and_b32_e32 v103, 0xffff0000, v51
	v_mul_f32_e32 v104, 0xbfb8aa3b, v96
	v_mul_f32_e32 v105, 0xbfb8aa3b, v97
	v_mul_f32_e32 v106, 0xbfb8aa3b, v98
	v_mul_f32_e32 v107, 0xbfb8aa3b, v99
	v_mul_f32_e32 v108, 0xbfb8aa3b, v100
	v_mul_f32_e32 v109, 0xbfb8aa3b, v101
	v_mul_f32_e32 v110, 0xbfb8aa3b, v102
	v_mul_f32_e32 v111, 0xbfb8aa3b, v103
	v_exp_f32_e32 v104, v104
	v_exp_f32_e32 v105, v105
	v_exp_f32_e32 v106, v106
	v_exp_f32_e32 v107, v107
	v_exp_f32_e32 v108, v108
	v_exp_f32_e32 v109, v109
	v_exp_f32_e32 v110, v110
	v_exp_f32_e32 v111, v111
	v_lshlrev_b32_e32 v112, 16, v32
	v_and_b32_e32 v113, 0xffff0000, v32
	v_lshlrev_b32_e32 v114, 16, v33
	v_and_b32_e32 v115, 0xffff0000, v33
	v_lshlrev_b32_e32 v116, 16, v34
	v_and_b32_e32 v117, 0xffff0000, v34
	v_lshlrev_b32_e32 v118, 16, v35
	v_and_b32_e32 v119, 0xffff0000, v35
	v_lshlrev_b32_e32 v120, 16, v40
	v_and_b32_e32 v121, 0xffff0000, v40
	v_lshlrev_b32_e32 v122, 16, v41
	v_and_b32_e32 v123, 0xffff0000, v41
	v_lshlrev_b32_e32 v124, 16, v42
	v_and_b32_e32 v125, 0xffff0000, v42
	v_lshlrev_b32_e32 v126, 16, v43
	v_and_b32_e32 v127, 0xffff0000, v43
	v_add_f32_e32 v112, v112, v120
	v_add_f32_e32 v113, v113, v121
	v_add_f32_e32 v114, v114, v122
	v_add_f32_e32 v115, v115, v123
	v_add_f32_e32 v116, v116, v124
	v_add_f32_e32 v117, v117, v125
	v_add_f32_e32 v118, v118, v126
	v_add_f32_e32 v119, v119, v127
	v_add_f32_e32 v104, 1.0, v104
	v_add_f32_e32 v105, 1.0, v105
	v_add_f32_e32 v106, 1.0, v106
	v_add_f32_e32 v107, 1.0, v107
	v_add_f32_e32 v108, 1.0, v108
	v_add_f32_e32 v109, 1.0, v109
	v_add_f32_e32 v110, 1.0, v110
	v_add_f32_e32 v111, 1.0, v111
	v_rcp_f32_e32 v104, v104
	v_rcp_f32_e32 v105, v105
	v_rcp_f32_e32 v106, v106
	v_rcp_f32_e32 v107, v107
	v_rcp_f32_e32 v108, v108
	v_rcp_f32_e32 v109, v109
	v_rcp_f32_e32 v110, v110
	v_rcp_f32_e32 v111, v111
	v_mul_f32_e32 v96, v96, v104
	v_mul_f32_e32 v97, v97, v105
	v_mul_f32_e32 v98, v98, v106
	v_mul_f32_e32 v99, v99, v107
	v_mul_f32_e32 v100, v100, v108
	v_mul_f32_e32 v101, v101, v109
	v_mul_f32_e32 v102, v102, v110
	v_mul_f32_e32 v103, v103, v111
	v_mul_f32_e32 v80, v112, v96
	v_mul_f32_e32 v81, v113, v97
	v_mul_f32_e32 v82, v114, v98
	v_mul_f32_e32 v83, v115, v99
	v_mul_f32_e32 v84, v116, v100
	v_mul_f32_e32 v85, v117, v101
	v_mul_f32_e32 v86, v118, v102
	v_mul_f32_e32 v87, v119, v103
	v_mul_f32_e32 v128, v80, v80
	v_fmac_f32_e32 v128, v81, v81
	v_fmac_f32_e32 v128, v82, v82
	v_fmac_f32_e32 v128, v83, v83
	v_fmac_f32_e32 v128, v84, v84
; #define wt16(p, v) wt16b(WSB, (p), (v))
; __device__ __forceinline__ u32x4 pack8(const float (&f)[8]) { u32x4 v; v.x = cvt_pk_bf16(f[0], f[1]); v.y = cvt_pk_bf16(f[2], f[3]); v.z = cvt_pk_bf16(f[4], f[5]); v.w = cvt_pk_bf16(f[6], f[7]); return v; }
; __device__ __forceinline__ float silu_f(float x) { return x * __builtin_amdgcn_rcpf(1.f + __expf(-x)); }
; __device__ __forceinline__ void ssd_combine_rows(CArgs a, int G) {
;     ...
;     auto finish = [&](int row, const u32x4 (&raw)[6]) {
;         float g[16]; float ss = 0.f;
; #pragma unroll
;         for (int hf = 0; hf < 2; ++hf) {
;             float f[8], bb[8], z[8];
;             unpack8(raw[3 * hf], f); unpack8(raw[3 * hf + 1], bb); unpack8(raw[3 * hf + 2], z);
; #pragma unroll
;             for (int e = 0; e < 8; ++e) { const float y = (f[e] + bb[e]) * silu_f(z[e]); g[8 * hf + e] = y; ss += y * y; }
;         }
;         ss += __shfl_xor(ss, 1); ss += __shfl_xor(ss, 2); ss += __shfl_xor(ss, 4); ss += __shfl_xor(ss, 8); ss += __shfl_xor(ss, 16);
;         const float r = rsqrtf(ss * (1.f / 512.f) + EPS);
;         float o0[8], o1[8];
; #pragma unroll
;         for (int e = 0; e < 8; ++e) { o0[e] = g[e] * r; o1[e] = g[8 + e] * r; }
;         wt16(Y + (size_t)row * 2048 + c0, pack8(o0)); wt16(Y + (size_t)row * 2048 + c0 + 8, pack8(o1));
;     };
;     for (int row = gw; row < T; row += 2 * NGW) {
;         const int row2 = row + NGW;
;         u32x4 ra[6], rb[6];
;         load(row, ra);
;         if (row2 < T) load(row2, rb);
;         finish(row, ra);
;         if (row2 < T) finish(row2, rb);
	v_fmac_f32_e32 v128, v85, v85
	v_fmac_f32_e32 v128, v86, v86
	v_fmac_f32_e32 v128, v87, v87
	v_lshlrev_b32_e32 v96, 16, v52
	v_and_b32_e32 v97, 0xffff0000, v52
	v_lshlrev_b32_e32 v98, 16, v53
	v_and_b32_e32 v99, 0xffff0000, v53
	v_lshlrev_b32_e32 v100, 16, v54
	v_and_b32_e32 v101, 0xffff0000, v54
	v_lshlrev_b32_e32 v102, 16, v55
	v_and_b32_e32 v103, 0xffff0000, v55
	v_mul_f32_e32 v104, 0xbfb8aa3b, v96
	v_mul_f32_e32 v105, 0xbfb8aa3b, v97
	v_mul_f32_e32 v106, 0xbfb8aa3b, v98
	v_mul_f32_e32 v107, 0xbfb8aa3b, v99
	v_mul_f32_e32 v108, 0xbfb8aa3b, v100
	v_mul_f32_e32 v109, 0xbfb8aa3b, v101
	v_mul_f32_e32 v110, 0xbfb8aa3b, v102
	v_mul_f32_e32 v111, 0xbfb8aa3b, v103
	v_exp_f32_e32 v104, v104
	v_exp_f32_e32 v105, v105
	v_exp_f32_e32 v106, v106
	v_exp_f32_e32 v107, v107
	v_exp_f32_e32 v108, v108
	v_exp_f32_e32 v109, v109
	v_exp_f32_e32 v110, v110
	v_exp_f32_e32 v111, v111
	v_lshlrev_b32_e32 v112, 16, v36
	v_and_b32_e32 v113, 0xffff0000, v36
	v_lshlrev_b32_e32 v114, 16, v37
	v_and_b32_e32 v115, 0xffff0000, v37
	v_lshlrev_b32_e32 v116, 16, v38
	v_and_b32_e32 v117, 0xffff0000, v38
	v_lshlrev_b32_e32 v118, 16, v39
	v_and_b32_e32 v119, 0xffff0000, v39
	v_lshlrev_b32_e32 v120, 16, v44
	v_and_b32_e32 v121, 0xffff0000, v44
	v_lshlrev_b32_e32 v122, 16, v45
	v_and_b32_e32 v123, 0xffff0000, v45
	v_lshlrev_b32_e32 v124, 16, v46
	v_and_b32_e32 v125, 0xffff0000, v46
	v_lshlrev_b32_e32 v126, 16, v47
	v_and_b32_e32 v127, 0xffff0000, v47
	v_add_f32_e32 v112, v112, v120
	v_add_f32_e32 v113, v113, v121
	v_add_f32_e32 v114, v114, v122
	v_add_f32_e32 v115, v115, v123
	v_add_f32_e32 v116, v116, v124
	v_add_f32_e32 v117, v117, v125
	v_add_f32_e32 v118, v118, v126
	v_add_f32_e32 v119, v119, v127
	v_add_f32_e32 v104, 1.0, v104
	v_add_f32_e32 v105, 1.0, v105
	v_add_f32_e32 v106, 1.0, v106
	v_add_f32_e32 v107, 1.0, v107
	v_add_f32_e32 v108, 1.0, v108
	v_add_f32_e32 v109, 1.0, v109
	v_add_f32_e32 v110, 1.0, v110
	v_add_f32_e32 v111, 1.0, v111
	v_rcp_f32_e32 v104, v104
	v_rcp_f32_e32 v105, v105
	v_rcp_f32_e32 v106, v106
	v_rcp_f32_e32 v107, v107
	v_rcp_f32_e32 v108, v108
	v_rcp_f32_e32 v109, v109
	v_rcp_f32_e32 v110, v110
	v_rcp_f32_e32 v111, v111
	v_mul_f32_e32 v96, v96, v104
	v_mul_f32_e32 v97, v97, v105
	v_mul_f32_e32 v98, v98, v106
	v_mul_f32_e32 v99, v99, v107
	v_mul_f32_e32 v100, v100, v108
	v_mul_f32_e32 v101, v101, v109
	v_mul_f32_e32 v102, v102, v110
	v_mul_f32_e32 v103, v103, v111
	v_mul_f32_e32 v88, v112, v96
	v_mul_f32_e32 v89, v113, v97
	v_mul_f32_e32 v90, v114, v98
	v_mul_f32_e32 v91, v115, v99
	v_mul_f32_e32 v92, v116, v100
	v_mul_f32_e32 v93, v117, v101
	v_mul_f32_e32 v94, v118, v102
	v_mul_f32_e32 v95, v119, v103
	v_mul_f32_e32 v129, v88, v88
	v_fmac_f32_e32 v129, v89, v89
	v_fmac_f32_e32 v129, v90, v90
	v_fmac_f32_e32 v129, v91, v91
	v_fmac_f32_e32 v129, v92, v92
	v_fmac_f32_e32 v129, v93, v93
	v_fmac_f32_e32 v129, v94, v94
	v_fmac_f32_e32 v129, v95, v95
	s_nop 1
	v_add_f32_dpp v128, v128, v128 row_shr:1 row_mask:0xf bank_mask:0xf bound_ctrl:0
	v_add_f32_dpp v129, v129, v129 row_shr:1 row_mask:0xf bank_mask:0xf bound_ctrl:0
	s_nop 0
	v_add_f32_dpp v128, v128, v128 row_shr:2 row_mask:0xf bank_mask:0xf bound_ctrl:0
	v_add_f32_dpp v129, v129, v129 row_shr:2 row_mask:0xf bank_mask:0xf bound_ctrl:0
	s_nop 0
	v_add_f32_dpp v128, v128, v128 row_shr:4 row_mask:0xf bank_mask:0xf bound_ctrl:0
	v_add_f32_dpp v129, v129, v129 row_shr:4 row_mask:0xf bank_mask:0xf bound_ctrl:0
	s_nop 0
	v_add_f32_dpp v128, v128, v128 row_shr:8 row_mask:0xf bank_mask:0xf bound_ctrl:0
	v_add_f32_dpp v129, v129, v129 row_shr:8 row_mask:0xf bank_mask:0xf bound_ctrl:0
	s_nop 0
	v_add_f32_dpp v128, v128, v128 row_bcast:15 row_mask:0xa bank_mask:0xf
	v_add_f32_dpp v129, v129, v129 row_bcast:15 row_mask:0xa bank_mask:0xf
	s_nop 0
	v_add_f32_dpp v128, v128, v128 row_bcast:31 row_mask:0xc bank_mask:0xf
	v_add_f32_dpp v129, v129, v129 row_bcast:31 row_mask:0xc bank_mask:0xf
	s_nop 0
	s_nop 0
	v_readlane_b32 s20, v128, 63
	v_readlane_b32 s21, v129, 63
	s_nop 1
	v_mov_b32_e32 v130, s20
	v_mov_b32_e32 v131, s21
	v_fmamk_f32 v130, v130, 0x3b000000, v245
	v_fmamk_f32 v131, v131, 0x3b000000, v245
	v_rsq_f32_e32 v130, v130
	v_rsq_f32_e32 v131, v131
	s_nop 0
	v_mul_f32_e32 v80, v80, v130
	v_mul_f32_e32 v81, v81, v130
	v_mul_f32_e32 v82, v82, v130
	v_mul_f32_e32 v83, v83, v130
	v_mul_f32_e32 v84, v84, v130
	v_mul_f32_e32 v85, v85, v130
	v_mul_f32_e32 v86, v86, v130
	v_mul_f32_e32 v87, v87, v130
	v_cvt_pk_bf16_f32 v80, v80, v81
	v_cvt_pk_bf16_f32 v81, v82, v83
	v_cvt_pk_bf16_f32 v82, v84, v85
	v_cvt_pk_bf16_f32 v83, v86, v87
	v_mul_f32_e32 v88, v88, v131
	v_mul_f32_e32 v89, v89, v131
	v_mul_f32_e32 v90, v90, v131
	v_mul_f32_e32 v91, v91, v131
	v_mul_f32_e32 v92, v92, v131
	v_mul_f32_e32 v93, v93, v131
	v_mul_f32_e32 v94, v94, v131
	v_mul_f32_e32 v95, v95, v131
	v_cvt_pk_bf16_f32 v88, v88, v89
	v_cvt_pk_bf16_f32 v89, v90, v91
	v_cvt_pk_bf16_f32 v90, v92, v93
	v_cvt_pk_bf16_f32 v91, v94, v95
	s_lshl_b32 s19, s10, 12
	s_add_u32 s19, s19, 0x10a00000
	buffer_store_dwordx4 v[80:83], v2, s[60:63], s19 offen sc1
	buffer_store_dwordx4 v[88:91], v2, s[60:63], s19 offen offset:1024 sc1
	s_mul_i32 s12, s11, 3
	s_add_i32 s12, s10, s12
	s_cmp_lt_u32 s12, 0x4000
	s_cselect_b32 s12, s12, s10
	s_lshl_b32 s16, s12, 12
	s_add_u32 s16, s16, 0x10a00000
	s_lshl_b32 s17, s12, 11
	s_add_u32 s17, s17, 0x18a00000
	s_mul_i32 s18, s12, 0x2400
	s_add_u32 s18, s18, 0x3a00000
	buffer_load_dwordx4 v[32:35], v2, s[60:63], s16 offen
	buffer_load_dwordx4 v[36:39], v2, s[60:63], s16 offen offset:1024
	buffer_load_dwordx4 v[40:43], v2, s[60:63], s17 offen
	buffer_load_dwordx4 v[44:47], v2, s[60:63], s17 offen offset:1024
	buffer_load_dwordx4 v[48:51], v2, s[60:63], s18 offen
	buffer_load_dwordx4 v[52:55], v2, s[60:63], s18 offen offset:1024
	s_add_i32 s10, s10, s11
	s_cmp_lt_u32 s10, 0x4000
	s_cbranch_scc0 .Lcmb_done
; __device__ __forceinline__ float silu_f(float x) { return x * __builtin_amdgcn_rcpf(1.f + __expf(-x)); }
; __device__ __forceinline__ void ssd_combine_rows(CArgs a, int G) {
;     ...
;     auto finish = [&](int row, const u32x4 (&raw)[6]) {
;         float g[16]; float ss = 0.f;
; #pragma unroll
;         for (int hf = 0; hf < 2; ++hf) {
;             float f[8], bb[8], z[8];
;             unpack8(raw[3 * hf], f); unpack8(raw[3 * hf + 1], bb); unpack8(raw[3 * hf + 2], z);
; #pragma unroll
;             for (int e = 0; e < 8; ++e) { const float y = (f[e] + bb[e]) * silu_f(z[e]); g[8 * hf + e] = y; ss += y * y; }
;         }
	s_waitcnt vmcnt(16)
	v_lshlrev_b32_e32 v96, 16, v72
	v_and_b32_e32 v97, 0xffff0000, v72
	v_lshlrev_b32_e32 v98, 16, v73
	v_and_b32_e32 v99, 0xffff0000, v73
	v_lshlrev_b32_e32 v100, 16, v74
	v_and_b32_e32 v101, 0xffff0000, v74
	v_lshlrev_b32_e32 v102, 16, v75
	v_and_b32_e32 v103, 0xffff0000, v75
	v_mul_f32_e32 v104, 0xbfb8aa3b, v96
	v_mul_f32_e32 v105, 0xbfb8aa3b, v97
	v_mul_f32_e32 v106, 0xbfb8aa3b, v98
	v_mul_f32_e32 v107, 0xbfb8aa3b, v99
	v_mul_f32_e32 v108, 0xbfb8aa3b, v100
	v_mul_f32_e32 v109, 0xbfb8aa3b, v101
	v_mul_f32_e32 v110, 0xbfb8aa3b, v102
	v_mul_f32_e32 v111, 0xbfb8aa3b, v103
	v_exp_f32_e32 v104, v104
	v_exp_f32_e32 v105, v105
	v_exp_f32_e32 v106, v106
	v_exp_f32_e32 v107, v107
	v_exp_f32_e32 v108, v108
	v_exp_f32_e32 v109, v109
	v_exp_f32_e32 v110, v110
	v_exp_f32_e32 v111, v111
	v_lshlrev_b32_e32 v112, 16, v56
	v_and_b32_e32 v113, 0xffff0000, v56
	v_lshlrev_b32_e32 v114, 16, v57
	v_and_b32_e32 v115, 0xffff0000, v57
	v_lshlrev_b32_e32 v116, 16, v58
	v_and_b32_e32 v117, 0xffff0000, v58
	v_lshlrev_b32_e32 v118, 16, v59
	v_and_b32_e32 v119, 0xffff0000, v59
	v_lshlrev_b32_e32 v120, 16, v64
	v_and_b32_e32 v121, 0xffff0000, v64
	v_lshlrev_b32_e32 v122, 16, v65
	v_and_b32_e32 v123, 0xffff0000, v65
	v_lshlrev_b32_e32 v124, 16, v66
	v_and_b32_e32 v125, 0xffff0000, v66
	v_lshlrev_b32_e32 v126, 16, v67
	v_and_b32_e32 v127, 0xffff0000, v67
	v_add_f32_e32 v112, v112, v120
	v_add_f32_e32 v113, v113, v121
	v_add_f32_e32 v114, v114, v122
	v_add_f32_e32 v115, v115, v123
	v_add_f32_e32 v116, v116, v124
	v_add_f32_e32 v117, v117, v125
	v_add_f32_e32 v118, v118, v126
	v_add_f32_e32 v119, v119, v127
	v_add_f32_e32 v104, 1.0, v104
	v_add_f32_e32 v105, 1.0, v105
	v_add_f32_e32 v106, 1.0, v106
	v_add_f32_e32 v107, 1.0, v107
	v_add_f32_e32 v108, 1.0, v108
	v_add_f32_e32 v109, 1.0, v109
	v_add_f32_e32 v110, 1.0, v110
	v_add_f32_e32 v111, 1.0, v111
	v_rcp_f32_e32 v104, v104
	v_rcp_f32_e32 v105, v105
	v_rcp_f32_e32 v106, v106
	v_rcp_f32_e32 v107, v107
	v_rcp_f32_e32 v108, v108
	v_rcp_f32_e32 v109, v109
	v_rcp_f32_e32 v110, v110
	v_rcp_f32_e32 v111, v111
	v_mul_f32_e32 v96, v96, v104
	v_mul_f32_e32 v97, v97, v105
	v_mul_f32_e32 v98, v98, v106
	v_mul_f32_e32 v99, v99, v107
	v_mul_f32_e32 v100, v100, v108
	v_mul_f32_e32 v101, v101, v109
	v_mul_f32_e32 v102, v102, v110
	v_mul_f32_e32 v103, v103, v111
	v_mul_f32_e32 v80, v112, v96
	v_mul_f32_e32 v81, v113, v97
	v_mul_f32_e32 v82, v114, v98
	v_mul_f32_e32 v83, v115, v99
	v_mul_f32_e32 v84, v116, v100
	v_mul_f32_e32 v85, v117, v101
	v_mul_f32_e32 v86, v118, v102
	v_mul_f32_e32 v87, v119, v103
	v_mul_f32_e32 v128, v80, v80
	v_fmac_f32_e32 v128, v81, v81
	v_fmac_f32_e32 v128, v82, v82
	v_fmac_f32_e32 v128, v83, v83
	v_fmac_f32_e32 v128, v84, v84
	v_fmac_f32_e32 v128, v85, v85
	v_fmac_f32_e32 v128, v86, v86
	v_fmac_f32_e32 v128, v87, v87
	v_lshlrev_b32_e32 v96, 16, v76
	v_and_b32_e32 v97, 0xffff0000, v76
	v_lshlrev_b32_e32 v98, 16, v77
	v_and_b32_e32 v99, 0xffff0000, v77
	v_lshlrev_b32_e32 v100, 16, v78
	v_and_b32_e32 v101, 0xffff0000, v78
	v_lshlrev_b32_e32 v102, 16, v79
	v_and_b32_e32 v103, 0xffff0000, v79
	v_mul_f32_e32 v104, 0xbfb8aa3b, v96
	v_mul_f32_e32 v105, 0xbfb8aa3b, v97
	v_mul_f32_e32 v106, 0xbfb8aa3b, v98
	v_mul_f32_e32 v107, 0xbfb8aa3b, v99
	v_mul_f32_e32 v108, 0xbfb8aa3b, v100
	v_mul_f32_e32 v109, 0xbfb8aa3b, v101
	v_mul_f32_e32 v110, 0xbfb8aa3b, v102
	v_mul_f32_e32 v111, 0xbfb8aa3b, v103
	v_exp_f32_e32 v104, v104
	v_exp_f32_e32 v105, v105
	v_exp_f32_e32 v106, v106
	v_exp_f32_e32 v107, v107
	v_exp_f32_e32 v108, v108
	v_exp_f32_e32 v109, v109
	v_exp_f32_e32 v110, v110
	v_exp_f32_e32 v111, v111
	v_lshlrev_b32_e32 v112, 16, v60
	v_and_b32_e32 v113, 0xffff0000, v60
	v_lshlrev_b32_e32 v114, 16, v61
	v_and_b32_e32 v115, 0xffff0000, v61
	v_lshlrev_b32_e32 v116, 16, v62
	v_and_b32_e32 v117, 0xffff0000, v62
	v_lshlrev_b32_e32 v118, 16, v63
	v_and_b32_e32 v119, 0xffff0000, v63
	v_lshlrev_b32_e32 v120, 16, v68
	v_and_b32_e32 v121, 0xffff0000, v68
	v_lshlrev_b32_e32 v122, 16, v69
	v_and_b32_e32 v123, 0xffff0000, v69
	v_lshlrev_b32_e32 v124, 16, v70
	v_and_b32_e32 v125, 0xffff0000, v70
	v_lshlrev_b32_e32 v126, 16, v71
	v_and_b32_e32 v127, 0xffff0000, v71
	v_add_f32_e32 v112, v112, v120
	v_add_f32_e32 v113, v113, v121
	v_add_f32_e32 v114, v114, v122
	v_add_f32_e32 v115, v115, v123
	v_add_f32_e32 v116, v116, v124
	v_add_f32_e32 v117, v117, v125
	v_add_f32_e32 v118, v118, v126
	v_add_f32_e32 v119, v119, v127
; #define wt16(p, v) wt16b(WSB, (p), (v))
; __device__ __forceinline__ u32x4 pack8(const float (&f)[8]) { u32x4 v; v.x = cvt_pk_bf16(f[0], f[1]); v.y = cvt_pk_bf16(f[2], f[3]); v.z = cvt_pk_bf16(f[4], f[5]); v.w = cvt_pk_bf16(f[6], f[7]); return v; }
; __device__ __forceinline__ void ssd_combine_rows(CArgs a, int G) {
;     ...
;         ss += __shfl_xor(ss, 1); ss += __shfl_xor(ss, 2); ss += __shfl_xor(ss, 4); ss += __shfl_xor(ss, 8); ss += __shfl_xor(ss, 16);
;         const float r = rsqrtf(ss * (1.f / 512.f) + EPS);
;         float o0[8], o1[8];
; #pragma unroll
;         for (int e = 0; e < 8; ++e) { o0[e] = g[e] * r; o1[e] = g[8 + e] * r; }
;         wt16(Y + (size_t)row * 2048 + c0, pack8(o0)); wt16(Y + (size_t)row * 2048 + c0 + 8, pack8(o1));
;     };
;     for (int row = gw; row < T; row += 2 * NGW) {
;         const int row2 = row + NGW;
;         u32x4 ra[6], rb[6];
;         load(row, ra);
;         if (row2 < T) load(row2, rb);
;         finish(row, ra);
;         if (row2 < T) finish(row2, rb);
;     }
	v_add_f32_e32 v104, 1.0, v104
	v_add_f32_e32 v105, 1.0, v105
	v_add_f32_e32 v106, 1.0, v106
	v_add_f32_e32 v107, 1.0, v107
	v_add_f32_e32 v108, 1.0, v108
	v_add_f32_e32 v109, 1.0, v109
	v_add_f32_e32 v110, 1.0, v110
	v_add_f32_e32 v111, 1.0, v111
	v_rcp_f32_e32 v104, v104
	v_rcp_f32_e32 v105, v105
	v_rcp_f32_e32 v106, v106
	v_rcp_f32_e32 v107, v107
	v_rcp_f32_e32 v108, v108
	v_rcp_f32_e32 v109, v109
	v_rcp_f32_e32 v110, v110
	v_rcp_f32_e32 v111, v111
	v_mul_f32_e32 v96, v96, v104
	v_mul_f32_e32 v97, v97, v105
	v_mul_f32_e32 v98, v98, v106
	v_mul_f32_e32 v99, v99, v107
	v_mul_f32_e32 v100, v100, v108
	v_mul_f32_e32 v101, v101, v109
	v_mul_f32_e32 v102, v102, v110
	v_mul_f32_e32 v103, v103, v111
	v_mul_f32_e32 v88, v112, v96
	v_mul_f32_e32 v89, v113, v97
	v_mul_f32_e32 v90, v114, v98
	v_mul_f32_e32 v91, v115, v99
	v_mul_f32_e32 v92, v116, v100
	v_mul_f32_e32 v93, v117, v101
	v_mul_f32_e32 v94, v118, v102
	v_mul_f32_e32 v95, v119, v103
	v_mul_f32_e32 v129, v88, v88
	v_fmac_f32_e32 v129, v89, v89
	v_fmac_f32_e32 v129, v90, v90
	v_fmac_f32_e32 v129, v91, v91
	v_fmac_f32_e32 v129, v92, v92
	v_fmac_f32_e32 v129, v93, v93
	v_fmac_f32_e32 v129, v94, v94
	v_fmac_f32_e32 v129, v95, v95
	s_nop 1
	v_add_f32_dpp v128, v128, v128 row_shr:1 row_mask:0xf bank_mask:0xf bound_ctrl:0
	v_add_f32_dpp v129, v129, v129 row_shr:1 row_mask:0xf bank_mask:0xf bound_ctrl:0
	s_nop 0
	v_add_f32_dpp v128, v128, v128 row_shr:2 row_mask:0xf bank_mask:0xf bound_ctrl:0
	v_add_f32_dpp v129, v129, v129 row_shr:2 row_mask:0xf bank_mask:0xf bound_ctrl:0
	s_nop 0
	v_add_f32_dpp v128, v128, v128 row_shr:4 row_mask:0xf bank_mask:0xf bound_ctrl:0
	v_add_f32_dpp v129, v129, v129 row_shr:4 row_mask:0xf bank_mask:0xf bound_ctrl:0
	s_nop 0
	v_add_f32_dpp v128, v128, v128 row_shr:8 row_mask:0xf bank_mask:0xf bound_ctrl:0
	v_add_f32_dpp v129, v129, v129 row_shr:8 row_mask:0xf bank_mask:0xf bound_ctrl:0
	s_nop 0
	v_add_f32_dpp v128, v128, v128 row_bcast:15 row_mask:0xa bank_mask:0xf
	v_add_f32_dpp v129, v129, v129 row_bcast:15 row_mask:0xa bank_mask:0xf
	s_nop 0
	v_add_f32_dpp v128, v128, v128 row_bcast:31 row_mask:0xc bank_mask:0xf
	v_add_f32_dpp v129, v129, v129 row_bcast:31 row_mask:0xc bank_mask:0xf
	s_nop 0
	s_nop 0
	v_readlane_b32 s20, v128, 63
	v_readlane_b32 s21, v129, 63
	s_nop 1
	v_mov_b32_e32 v130, s20
	v_mov_b32_e32 v131, s21
	v_fmamk_f32 v130, v130, 0x3b000000, v245
	v_fmamk_f32 v131, v131, 0x3b000000, v245
	v_rsq_f32_e32 v130, v130
	v_rsq_f32_e32 v131, v131
	s_nop 0
	v_mul_f32_e32 v80, v80, v130
	v_mul_f32_e32 v81, v81, v130
	v_mul_f32_e32 v82, v82, v130
	v_mul_f32_e32 v83, v83, v130
	v_mul_f32_e32 v84, v84, v130
	v_mul_f32_e32 v85, v85, v130
	v_mul_f32_e32 v86, v86, v130
	v_mul_f32_e32 v87, v87, v130
	v_cvt_pk_bf16_f32 v80, v80, v81
	v_cvt_pk_bf16_f32 v81, v82, v83
	v_cvt_pk_bf16_f32 v82, v84, v85
	v_cvt_pk_bf16_f32 v83, v86, v87
	v_mul_f32_e32 v88, v88, v131
	v_mul_f32_e32 v89, v89, v131
	v_mul_f32_e32 v90, v90, v131
	v_mul_f32_e32 v91, v91, v131
	v_mul_f32_e32 v92, v92, v131
	v_mul_f32_e32 v93, v93, v131
	v_mul_f32_e32 v94, v94, v131
	v_mul_f32_e32 v95, v95, v131
	v_cvt_pk_bf16_f32 v88, v88, v89
	v_cvt_pk_bf16_f32 v89, v90, v91
	v_cvt_pk_bf16_f32 v90, v92, v93
	v_cvt_pk_bf16_f32 v91, v94, v95
	s_lshl_b32 s19, s10, 12
	s_add_u32 s19, s19, 0x10a00000
	buffer_store_dwordx4 v[80:83], v2, s[60:63], s19 offen sc1
	buffer_store_dwordx4 v[88:91], v2, s[60:63], s19 offen offset:1024 sc1
	s_mul_i32 s12, s11, 3
	s_add_i32 s12, s10, s12
	s_cmp_lt_u32 s12, 0x4000
	s_cselect_b32 s12, s12, s10
	s_lshl_b32 s16, s12, 12
	s_add_u32 s16, s16, 0x10a00000
	s_lshl_b32 s17, s12, 11
	s_add_u32 s17, s17, 0x18a00000
	s_mul_i32 s18, s12, 0x2400
	s_add_u32 s18, s18, 0x3a00000
	buffer_load_dwordx4 v[56:59], v2, s[60:63], s16 offen
	buffer_load_dwordx4 v[60:63], v2, s[60:63], s16 offen offset:1024
	buffer_load_dwordx4 v[64:67], v2, s[60:63], s17 offen
	buffer_load_dwordx4 v[68:71], v2, s[60:63], s17 offen offset:1024
	buffer_load_dwordx4 v[72:75], v2, s[60:63], s18 offen
	buffer_load_dwordx4 v[76:79], v2, s[60:63], s18 offen offset:1024
	s_add_i32 s10, s10, s11
	s_cmp_lt_u32 s10, 0x4000
	s_cbranch_scc0 .Lcmb_done
	s_branch .Lcmb_loop
.Lcmb_done:
	s_waitcnt vmcnt(0)
.LBB0_90:
	s_or_b64 exec, exec, s[16:17]
	v_readlane_b32 s2, v255, 42
	s_nop 3
	s_cmp_eq_u32 s2, 1
	s_cbranch_scc0 .Lp5_done
	s_mov_b32 s2, 2
	s_nop 1
	v_writelane_b32 v255, s2, 42
	s_branch .Lp5_attn_entry
